# v105: v102 + the two waits that end every load segment merged into one s_waitcnt, priority raise issued before it
# baseline (speedup 1.0000x reference)
; #define PG8_STAGE(bufoff, gbase, voff) do { _Pragma("unroll") for (int _i = 0; _i < 2; ++_i) \
;         __builtin_amdgcn_global_load_lds((const unsigned*)((const char*)(gbase) + (voff)[_i]), (PG8_LAS unsigned*)(lds + (bufoff) + ldsw + _i * 8192), 16, 0, 0); } while (0)
; #define PG8_LDA(dst, b, h) do { _Pragma("unroll") for (int m = 0; m < 4; ++m) _Pragma("unroll") for (int k = 0; k < 2; ++k) dst[m][k] = *(const PG8_LAS bf16x8*)(lds + PG8_SA(b, h) + aoff + m * 2048 + k * 1024); } while (0)
; #define PG8_LDB(dst, b, h) do { _Pragma("unroll") for (int n = 0; n < 2; ++n) _Pragma("unroll") for (int k = 0; k < 2; ++k) dst[n][k] = *(const PG8_LAS bf16x8*)(lds + PG8_SB(b, h) + boff + n * 2048 + k * 1024); } while (0)
; #define PG8_WAIT_V(n) asm volatile("s_waitcnt vmcnt(" #n ")" ::: "memory")
; #define PG8_WAIT_L(n) asm volatile("s_waitcnt lgkmcnt(" #n ")" ::: "memory")
; #define PG8_BAR __builtin_amdgcn_s_barrier()
; #define PG8_SCHED __builtin_amdgcn_sched_barrier(0)
; template <class Epi, class Sched, bool ALIGN_EPI, int LMASK = -1, int LMASKB = LMASK>
; __device__ __forceinline__ void gemm_phase(PG8_LAS unsigned char* lds, const Gemm g, const Sched& S, const Epi& E) {
;     ...
;         const bool has_next = S.next(ui + 1, nxt);
;         const char* nA = has_next ? (const char*)g.A + (size_t)(nxt.pm & LMASK) * tstepA : cA; const char* nB = has_next ? (const char*)g.Bt + (size_t)nxt.pm * g.b_pm_stride + (size_t)(nxt.pn & LMASKB) * tstepB : cB;
;         for (int t = 0; t < nt; t += 2) {
;             const bool last = (t == nt - 2);
;             const char* a1 = cA + (size_t)(t + 1) * kstepA;
;             const char* a2 = last ? nA : cA + (size_t)(t + 2) * kstepA; const char* b2 = last ? nB : cB + (size_t)(t + 2) * kstepB;
;             const char* a3 = a2 + kstepA; const char* b3 = b2 + kstepB;
;             PG8_LDB(B0, 0, 0); PG8_LDB(B1, 0, 1); PG8_SCHED; PG8_LDA(At, 0, 0); PG8_STAGE(PG8_SA(1, 1), a1 + hstepA, voffA);
;             PG8_WAIT_V(8); PG8_WAIT_L(0); PG8_BAR; PG8_MMA(0, 0, At, B0); PG8_MMA(0, 1, At, B1); PG8_BAR; PG8_SCHED;
;             PG8_LDA(At, 0, 1); PG8_STAGE(PG8_SB(0, 0), b2, voffB); PG8_STAGE(PG8_SB(0, 1), b2 + hstepB, voffB); PG8_STAGE(PG8_SA(0, 0), a2, voffA);
;             PG8_WAIT_V(8); PG8_WAIT_L(0); PG8_BAR; PG8_MMA(1, 0, At, B0); PG8_MMA(1, 1, At, B1); PG8_BAR; PG8_SCHED;
.LBB0_206:
	s_ashr_i32 s17, s16, 31
	s_lshl_b64 s[2:3], s[16:17], 17
	s_add_u32 s20, s1, s2
	s_addc_u32 s21, s33, s3
	s_and_b64 s[2:3], s[4:5], exec
	s_cselect_b32 s29, s21, s23
	s_cselect_b32 s28, s20, s22
	s_lshl_b64 s[2:3], s[16:17], 21
	s_add_u32 s17, s36, s2
	ds_read_b128 v[2:5], v142
	ds_read_b128 v[6:9], v142 offset:1024
	ds_read_b128 v[10:13], v142 offset:2048
	ds_read_b128 v[14:17], v142 offset:3072
	ds_read_b128 v[18:21], v143
	ds_read_b128 v[22:25], v143 offset:1024
	ds_read_b128 v[26:29], v143 offset:2048
	ds_read_b128 v[30:33], v143 offset:3072
	s_addc_u32 s26, s37, s3
	s_ashr_i32 s15, s14, 31
	s_lshl_b64 s[2:3], s[14:15], 17
	s_add_u32 s2, s17, s2
	s_addc_u32 s3, s26, s3
	s_and_b64 s[26:27], s[4:5], exec
	s_cselect_b32 s27, s3, s25
	s_cselect_b32 s26, s2, s24
	s_add_u32 s34, s22, 0x1000
	s_addc_u32 s35, s23, 0
	s_add_u32 s54, s24, 0x1000
	s_addc_u32 s55, s25, 0
	s_add_u32 s30, s22, 0x1800
	s_addc_u32 s31, s23, 0
	s_add_u32 s56, s22, 0x10800
	s_addc_u32 s57, s23, 0
	s_mov_b32 m0, s50
	v_lshl_add_u64 v[66:67], s[56:57], 0, v[130:131]
	ds_read_b128 v[34:37], v144
	ds_read_b128 v[38:41], v144 offset:1024
	ds_read_b128 v[42:45], v144 offset:2048
	ds_read_b128 v[46:49], v144 offset:3072
	ds_read_b128 v[50:53], v144 offset:4096
	ds_read_b128 v[54:57], v144 offset:5120
	ds_read_b128 v[58:61], v144 offset:6144
	ds_read_b128 v[62:65], v144 offset:7168
	global_load_lds_dwordx4 v[66:67], off
	v_lshl_add_u64 v[66:67], s[56:57], 0, v[132:133]
	s_mov_b32 m0, s51
	s_nop 0
	global_load_lds_dwordx4 v[66:67], off
	s_setprio 1
	s_waitcnt vmcnt(8) lgkmcnt(0)
	s_barrier
	v_mfma_f32_16x16x32_bf16 v[66:69], v[2:5], v[34:37], 0
	v_mfma_f32_16x16x32_bf16 v[70:73], v[10:13], v[34:37], 0
	v_mfma_f32_16x16x32_bf16 v[74:77], v[2:5], v[42:45], 0
	v_mfma_f32_16x16x32_bf16 v[78:81], v[10:13], v[42:45], 0
	v_mfma_f32_16x16x32_bf16 v[82:85], v[2:5], v[50:53], 0
	v_mfma_f32_16x16x32_bf16 v[86:89], v[10:13], v[50:53], 0
	v_mfma_f32_16x16x32_bf16 v[90:93], v[2:5], v[58:61], 0
	v_mfma_f32_16x16x32_bf16 v[94:97], v[10:13], v[58:61], 0
	v_mfma_f32_16x16x32_bf16 v[66:69], v[6:9], v[38:41], v[66:69]
	v_mfma_f32_16x16x32_bf16 v[70:73], v[14:17], v[38:41], v[70:73]
	v_mfma_f32_16x16x32_bf16 v[74:77], v[6:9], v[46:49], v[74:77]
	v_mfma_f32_16x16x32_bf16 v[78:81], v[14:17], v[46:49], v[78:81]
	v_mfma_f32_16x16x32_bf16 v[82:85], v[6:9], v[54:57], v[82:85]
	v_mfma_f32_16x16x32_bf16 v[86:89], v[14:17], v[54:57], v[86:89]
	v_mfma_f32_16x16x32_bf16 v[90:93], v[6:9], v[62:65], v[90:93]
	v_mfma_f32_16x16x32_bf16 v[94:97], v[14:17], v[62:65], v[94:97]
	v_mfma_f32_16x16x32_bf16 v[98:101], v[18:21], v[34:37], 0
	v_mfma_f32_16x16x32_bf16 v[34:37], v[26:29], v[34:37], 0
	v_mfma_f32_16x16x32_bf16 v[98:101], v[22:25], v[38:41], v[98:101]
	v_mfma_f32_16x16x32_bf16 v[34:37], v[30:33], v[38:41], v[34:37]
	v_mfma_f32_16x16x32_bf16 v[38:41], v[18:21], v[42:45], 0
	v_mfma_f32_16x16x32_bf16 v[42:45], v[26:29], v[42:45], 0
	v_mfma_f32_16x16x32_bf16 v[38:41], v[22:25], v[46:49], v[38:41]
	v_mfma_f32_16x16x32_bf16 v[42:45], v[30:33], v[46:49], v[42:45]
	v_mfma_f32_16x16x32_bf16 v[46:49], v[18:21], v[50:53], 0
	v_mfma_f32_16x16x32_bf16 v[50:53], v[26:29], v[50:53], 0
	v_mfma_f32_16x16x32_bf16 v[46:49], v[22:25], v[54:57], v[46:49]
	v_mfma_f32_16x16x32_bf16 v[50:53], v[30:33], v[54:57], v[50:53]
	v_mfma_f32_16x16x32_bf16 v[54:57], v[18:21], v[58:61], 0
	v_mfma_f32_16x16x32_bf16 v[58:61], v[26:29], v[58:61], 0
	v_mfma_f32_16x16x32_bf16 v[54:57], v[22:25], v[62:65], v[54:57]
	v_mfma_f32_16x16x32_bf16 v[58:61], v[30:33], v[62:65], v[58:61]
	s_barrier
	s_setprio 0
	s_mov_b32 m0, s52
	v_lshl_add_u64 v[146:147], s[54:55], 0, v[130:131]
	s_add_i32 s15, s52, 0x2000
	ds_read_b128 v[62:65], v144 offset:16384
	ds_read_b128 v[102:105], v144 offset:17408
	ds_read_b128 v[106:109], v144 offset:18432
	ds_read_b128 v[110:113], v144 offset:19456
	ds_read_b128 v[114:117], v144 offset:20480
	ds_read_b128 v[118:121], v144 offset:21504
	ds_read_b128 v[122:125], v144 offset:22528
	ds_read_b128 v[126:129], v144 offset:23552
	global_load_lds_dwordx4 v[146:147], off
	v_lshl_add_u64 v[146:147], s[54:55], 0, v[132:133]
	s_add_u32 s54, s24, 0x11000
	s_mov_b32 m0, s15
	s_addc_u32 s55, s25, 0
	s_add_i32 s17, s48, s38
	global_load_lds_dwordx4 v[146:147], off
	v_lshl_add_u64 v[146:147], s[54:55], 0, v[130:131]
	s_mov_b32 m0, s17
	s_nop 0
	global_load_lds_dwordx4 v[146:147], off
	v_lshl_add_u64 v[146:147], s[54:55], 0, v[132:133]
	s_add_i32 s54, s17, 0x2000
	s_mov_b32 m0, s54
	s_nop 0
	global_load_lds_dwordx4 v[146:147], off
	v_lshl_add_u64 v[146:147], s[34:35], 0, v[130:131]
	s_mov_b32 m0, s19
	s_nop 0
	global_load_lds_dwordx4 v[146:147], off
	v_lshl_add_u64 v[146:147], s[34:35], 0, v[132:133]
	s_mov_b32 m0, s39
	s_nop 0
	global_load_lds_dwordx4 v[146:147], off
	s_setprio 1
	s_waitcnt vmcnt(8) lgkmcnt(0)
	s_barrier
; #define PG8_STAGE(bufoff, gbase, voff) do { _Pragma("unroll") for (int _i = 0; _i < 2; ++_i) \
;         __builtin_amdgcn_global_load_lds((const unsigned*)((const char*)(gbase) + (voff)[_i]), (PG8_LAS unsigned*)(lds + (bufoff) + ldsw + _i * 8192), 16, 0, 0); } while (0)
; #define PG8_LDA(dst, b, h) do { _Pragma("unroll") for (int m = 0; m < 4; ++m) _Pragma("unroll") for (int k = 0; k < 2; ++k) dst[m][k] = *(const PG8_LAS bf16x8*)(lds + PG8_SA(b, h) + aoff + m * 2048 + k * 1024); } while (0)
; #define PG8_LDB(dst, b, h) do { _Pragma("unroll") for (int n = 0; n < 2; ++n) _Pragma("unroll") for (int k = 0; k < 2; ++k) dst[n][k] = *(const PG8_LAS bf16x8*)(lds + PG8_SB(b, h) + boff + n * 2048 + k * 1024); } while (0)
; #define PG8_MMA(ai, bj, At, Bt) do { __builtin_amdgcn_s_setprio(1); _Pragma("unroll") for (int m = 0; m < 4; ++m) _Pragma("unroll") for (int n = 0; n < 2; ++n) _Pragma("unroll") for (int k = 0; k < 2; ++k) \
;         acc[ai][bj][m][n] = __builtin_amdgcn_mfma_f32_16x16x32_bf16(Bt[n][k], At[m][k], acc[ai][bj][m][n], 0, 0, 0); __builtin_amdgcn_s_setprio(0); } while (0)
; #define PG8_WAIT_V(n) asm volatile("s_waitcnt vmcnt(" #n ")" ::: "memory")
; #define PG8_WAIT_L(n) asm volatile("s_waitcnt lgkmcnt(" #n ")" ::: "memory")
; #define PG8_BAR __builtin_amdgcn_s_barrier()
; #define PG8_SCHED __builtin_amdgcn_sched_barrier(0)
; template <class Epi, class Sched, bool ALIGN_EPI, int LMASK = -1, int LMASKB = LMASK>
; __device__ __forceinline__ void gemm_phase(PG8_LAS unsigned char* lds, const Gemm g, const Sched& S, const Epi& E) {
;     ...
;             PG8_WAIT_V(8); PG8_WAIT_L(0); PG8_BAR; PG8_MMA(1, 0, At, B0); PG8_MMA(1, 1, At, B1); PG8_BAR; PG8_SCHED;
;             PG8_LDB(B0, 1, 0); PG8_LDB(B1, 1, 1); PG8_SCHED; PG8_LDA(At, 1, 0); PG8_STAGE(PG8_SA(0, 1), a2 + hstepA, voffA);
;             PG8_WAIT_V(8); PG8_WAIT_L(0); PG8_BAR; PG8_MMA(0, 0, At, B0); PG8_MMA(0, 1, At, B1); PG8_BAR; PG8_SCHED;
;             PG8_LDA(At, 1, 1); PG8_STAGE(PG8_SB(1, 0), b3, voffB); PG8_STAGE(PG8_SB(1, 1), b3 + hstepB, voffB); PG8_STAGE(PG8_SA(1, 0), a3, voffA);
	v_mfma_f32_16x16x32_bf16 v[146:149], v[2:5], v[62:65], 0
	v_mfma_f32_16x16x32_bf16 v[154:157], v[2:5], v[106:109], 0
	v_mfma_f32_16x16x32_bf16 v[162:165], v[2:5], v[114:117], 0
	v_mfma_f32_16x16x32_bf16 v[2:5], v[2:5], v[122:125], 0
	v_mfma_f32_16x16x32_bf16 v[146:149], v[6:9], v[102:105], v[146:149]
	v_mfma_f32_16x16x32_bf16 v[154:157], v[6:9], v[110:113], v[154:157]
	v_mfma_f32_16x16x32_bf16 v[162:165], v[6:9], v[118:121], v[162:165]
	v_mfma_f32_16x16x32_bf16 v[2:5], v[6:9], v[126:129], v[2:5]
	v_mfma_f32_16x16x32_bf16 v[6:9], v[10:13], v[122:125], 0
	v_mfma_f32_16x16x32_bf16 v[150:153], v[10:13], v[62:65], 0
	v_mfma_f32_16x16x32_bf16 v[158:161], v[10:13], v[106:109], 0
	v_mfma_f32_16x16x32_bf16 v[166:169], v[10:13], v[114:117], 0
	v_mfma_f32_16x16x32_bf16 v[6:9], v[14:17], v[126:129], v[6:9]
	v_mfma_f32_16x16x32_bf16 v[150:153], v[14:17], v[102:105], v[150:153]
	v_mfma_f32_16x16x32_bf16 v[158:161], v[14:17], v[110:113], v[158:161]
	v_mfma_f32_16x16x32_bf16 v[166:169], v[14:17], v[118:121], v[166:169]
	v_mfma_f32_16x16x32_bf16 v[10:13], v[18:21], v[62:65], 0
	v_mfma_f32_16x16x32_bf16 v[14:17], v[26:29], v[62:65], 0
	v_mfma_f32_16x16x32_bf16 v[10:13], v[22:25], v[102:105], v[10:13]
	v_mfma_f32_16x16x32_bf16 v[14:17], v[30:33], v[102:105], v[14:17]
	v_mfma_f32_16x16x32_bf16 v[62:65], v[18:21], v[106:109], 0
	v_mfma_f32_16x16x32_bf16 v[102:105], v[26:29], v[106:109], 0
	v_mfma_f32_16x16x32_bf16 v[106:109], v[18:21], v[114:117], 0
	v_mfma_f32_16x16x32_bf16 v[18:21], v[18:21], v[122:125], 0
	v_mfma_f32_16x16x32_bf16 v[62:65], v[22:25], v[110:113], v[62:65]
	v_mfma_f32_16x16x32_bf16 v[102:105], v[30:33], v[110:113], v[102:105]
	v_mfma_f32_16x16x32_bf16 v[106:109], v[22:25], v[118:121], v[106:109]
	v_mfma_f32_16x16x32_bf16 v[110:113], v[26:29], v[114:117], 0
	v_mfma_f32_16x16x32_bf16 v[18:21], v[22:25], v[126:129], v[18:21]
	v_mfma_f32_16x16x32_bf16 v[22:25], v[26:29], v[122:125], 0
	v_mfma_f32_16x16x32_bf16 v[110:113], v[30:33], v[118:121], v[110:113]
	v_mfma_f32_16x16x32_bf16 v[22:25], v[30:33], v[126:129], v[22:25]
	s_barrier
	s_setprio 0
	s_add_i32 s55, 0, 0x18000
	s_add_i32 s58, 0, 0x1c000
	v_add_u32_e32 v134, s55, v1
	v_add_u32_e32 v222, s58, v1
	ds_read_b128 v[26:29], v134
	ds_read_b128 v[30:33], v134 offset:1024
	ds_read_b128 v[114:117], v134 offset:2048
	ds_read_b128 v[118:121], v134 offset:3072
	ds_read_b128 v[122:125], v222
	ds_read_b128 v[126:129], v222 offset:1024
	ds_read_b128 v[170:173], v222 offset:2048
	ds_read_b128 v[174:177], v222 offset:3072
	s_add_u32 s34, s22, 0x11000
	s_addc_u32 s35, s23, 0
	s_mov_b32 m0, s40
	v_lshl_add_u64 v[210:211], s[34:35], 0, v[130:131]
	ds_read_b128 v[178:181], v144 offset:32768
	ds_read_b128 v[182:185], v144 offset:33792
	ds_read_b128 v[186:189], v144 offset:34816
	ds_read_b128 v[190:193], v144 offset:35840
	ds_read_b128 v[194:197], v144 offset:36864
	ds_read_b128 v[198:201], v144 offset:37888
	ds_read_b128 v[202:205], v144 offset:38912
	ds_read_b128 v[206:209], v144 offset:39936
	global_load_lds_dwordx4 v[210:211], off
	v_lshl_add_u64 v[210:211], s[34:35], 0, v[132:133]
	s_mov_b32 m0, s41
	s_nop 0
	global_load_lds_dwordx4 v[210:211], off
	s_setprio 1
	s_waitcnt vmcnt(8) lgkmcnt(0)
	s_barrier
	v_mfma_f32_16x16x32_bf16 v[66:69], v[26:29], v[178:181], v[66:69]
	v_mfma_f32_16x16x32_bf16 v[70:73], v[114:117], v[178:181], v[70:73]
	v_mfma_f32_16x16x32_bf16 v[74:77], v[26:29], v[186:189], v[74:77]
	v_mfma_f32_16x16x32_bf16 v[78:81], v[114:117], v[186:189], v[78:81]
	v_mfma_f32_16x16x32_bf16 v[82:85], v[26:29], v[194:197], v[82:85]
	v_mfma_f32_16x16x32_bf16 v[86:89], v[114:117], v[194:197], v[86:89]
	v_mfma_f32_16x16x32_bf16 v[90:93], v[26:29], v[202:205], v[90:93]
	v_mfma_f32_16x16x32_bf16 v[94:97], v[114:117], v[202:205], v[94:97]
	v_mfma_f32_16x16x32_bf16 v[66:69], v[30:33], v[182:185], v[66:69]
	v_mfma_f32_16x16x32_bf16 v[70:73], v[118:121], v[182:185], v[70:73]
	v_mfma_f32_16x16x32_bf16 v[74:77], v[30:33], v[190:193], v[74:77]
	v_mfma_f32_16x16x32_bf16 v[78:81], v[118:121], v[190:193], v[78:81]
	v_mfma_f32_16x16x32_bf16 v[82:85], v[30:33], v[198:201], v[82:85]
	v_mfma_f32_16x16x32_bf16 v[86:89], v[118:121], v[198:201], v[86:89]
	v_mfma_f32_16x16x32_bf16 v[90:93], v[30:33], v[206:209], v[90:93]
	v_mfma_f32_16x16x32_bf16 v[94:97], v[118:121], v[206:209], v[94:97]
	v_mfma_f32_16x16x32_bf16 v[98:101], v[122:125], v[178:181], v[98:101]
	v_mfma_f32_16x16x32_bf16 v[34:37], v[170:173], v[178:181], v[34:37]
	v_mfma_f32_16x16x32_bf16 v[38:41], v[122:125], v[186:189], v[38:41]
	v_mfma_f32_16x16x32_bf16 v[42:45], v[170:173], v[186:189], v[42:45]
	v_mfma_f32_16x16x32_bf16 v[46:49], v[122:125], v[194:197], v[46:49]
	v_mfma_f32_16x16x32_bf16 v[50:53], v[170:173], v[194:197], v[50:53]
	v_mfma_f32_16x16x32_bf16 v[54:57], v[122:125], v[202:205], v[54:57]
	v_mfma_f32_16x16x32_bf16 v[58:61], v[170:173], v[202:205], v[58:61]
	v_mfma_f32_16x16x32_bf16 v[98:101], v[126:129], v[182:185], v[98:101]
	v_mfma_f32_16x16x32_bf16 v[34:37], v[174:177], v[182:185], v[34:37]
	v_mfma_f32_16x16x32_bf16 v[38:41], v[126:129], v[190:193], v[38:41]
	v_mfma_f32_16x16x32_bf16 v[42:45], v[174:177], v[190:193], v[42:45]
	v_mfma_f32_16x16x32_bf16 v[46:49], v[126:129], v[198:201], v[46:49]
	v_mfma_f32_16x16x32_bf16 v[50:53], v[174:177], v[198:201], v[50:53]
	v_mfma_f32_16x16x32_bf16 v[54:57], v[126:129], v[206:209], v[54:57]
	v_mfma_f32_16x16x32_bf16 v[58:61], v[174:177], v[206:209], v[58:61]
	s_barrier
; #define PG8_STAGE(bufoff, gbase, voff) do { _Pragma("unroll") for (int _i = 0; _i < 2; ++_i) \
;         __builtin_amdgcn_global_load_lds((const unsigned*)((const char*)(gbase) + (voff)[_i]), (PG8_LAS unsigned*)(lds + (bufoff) + ldsw + _i * 8192), 16, 0, 0); } while (0)
; #define PG8_LDA(dst, b, h) do { _Pragma("unroll") for (int m = 0; m < 4; ++m) _Pragma("unroll") for (int k = 0; k < 2; ++k) dst[m][k] = *(const PG8_LAS bf16x8*)(lds + PG8_SA(b, h) + aoff + m * 2048 + k * 1024); } while (0)
; #define PG8_LDB(dst, b, h) do { _Pragma("unroll") for (int n = 0; n < 2; ++n) _Pragma("unroll") for (int k = 0; k < 2; ++k) dst[n][k] = *(const PG8_LAS bf16x8*)(lds + PG8_SB(b, h) + boff + n * 2048 + k * 1024); } while (0)
; #define PG8_MMA(ai, bj, At, Bt) do { __builtin_amdgcn_s_setprio(1); _Pragma("unroll") for (int m = 0; m < 4; ++m) _Pragma("unroll") for (int n = 0; n < 2; ++n) _Pragma("unroll") for (int k = 0; k < 2; ++k) \
;         acc[ai][bj][m][n] = __builtin_amdgcn_mfma_f32_16x16x32_bf16(Bt[n][k], At[m][k], acc[ai][bj][m][n], 0, 0, 0); __builtin_amdgcn_s_setprio(0); } while (0)
; #define PG8_BAR __builtin_amdgcn_s_barrier()
; template <class Epi, class Sched, bool ALIGN_EPI, int LMASK = -1, int LMASKB = LMASK>
; __device__ __forceinline__ void gemm_phase(PG8_LAS unsigned char* lds, const Gemm g, const Sched& S, const Epi& E) {
;     ...
;             PG8_LDB(B0, 0, 0); PG8_LDB(B1, 0, 1); PG8_SCHED; PG8_LDA(At, 0, 0); PG8_STAGE(PG8_SA(1, 1), a1 + hstepA, voffA);
;             PG8_WAIT_V(8); PG8_WAIT_L(0); PG8_BAR; PG8_MMA(0, 0, At, B0); PG8_MMA(0, 1, At, B1); PG8_BAR; PG8_SCHED;
;             PG8_LDA(At, 0, 1); PG8_STAGE(PG8_SB(0, 0), b2, voffB); PG8_STAGE(PG8_SB(0, 1), b2 + hstepB, voffB); PG8_STAGE(PG8_SA(0, 0), a2, voffA);
;             PG8_WAIT_V(8); PG8_WAIT_L(0); PG8_BAR; PG8_MMA(1, 0, At, B0); PG8_MMA(1, 1, At, B1); PG8_BAR; PG8_SCHED;
;             PG8_LDB(B0, 1, 0); PG8_LDB(B1, 1, 1); PG8_SCHED; PG8_LDA(At, 1, 0); PG8_STAGE(PG8_SA(0, 1), a2 + hstepA, voffA);
;             PG8_WAIT_V(8); PG8_WAIT_L(0); PG8_BAR; PG8_MMA(0, 0, At, B0); PG8_MMA(0, 1, At, B1); PG8_BAR; PG8_SCHED;
;             PG8_LDA(At, 1, 1); PG8_STAGE(PG8_SB(1, 0), b3, voffB); PG8_STAGE(PG8_SB(1, 1), b3 + hstepB, voffB); PG8_STAGE(PG8_SA(1, 0), a3, voffA);
;             PG8_WAIT_V(8); PG8_WAIT_L(0); PG8_BAR; PG8_MMA(1, 0, At, B0); PG8_MMA(1, 1, At, B1); PG8_BAR; PG8_SCHED;
	s_setprio 0
	s_add_u32 s56, s24, 0x1800
	s_addc_u32 s57, s25, 0
	s_add_i32 s35, s55, s38
	v_lshl_add_u64 v[210:211], s[56:57], 0, v[130:131]
	s_mov_b32 m0, s35
	s_add_i32 s34, s35, 0x2000
	ds_read_b128 v[178:181], v144 offset:49152
	ds_read_b128 v[182:185], v144 offset:50176
	ds_read_b128 v[186:189], v144 offset:51200
	ds_read_b128 v[190:193], v144 offset:52224
	ds_read_b128 v[194:197], v144 offset:53248
	ds_read_b128 v[198:201], v144 offset:54272
	ds_read_b128 v[202:205], v144 offset:55296
	ds_read_b128 v[206:209], v144 offset:56320
	global_load_lds_dwordx4 v[210:211], off
	v_lshl_add_u64 v[210:211], s[56:57], 0, v[132:133]
	s_add_u32 s56, s24, 0x11800
	s_mov_b32 m0, s34
	s_addc_u32 s57, s25, 0
	s_add_i32 s24, s58, s38
	global_load_lds_dwordx4 v[210:211], off
	v_lshl_add_u64 v[210:211], s[56:57], 0, v[130:131]
	s_mov_b32 m0, s24
	s_add_i32 s25, s24, 0x2000
	global_load_lds_dwordx4 v[210:211], off
	v_lshl_add_u64 v[210:211], s[56:57], 0, v[132:133]
	s_mov_b32 m0, s25
	s_nop 0
	global_load_lds_dwordx4 v[210:211], off
	v_lshl_add_u64 v[210:211], s[30:31], 0, v[130:131]
	s_mov_b32 m0, s44
	s_nop 0
	global_load_lds_dwordx4 v[210:211], off
	v_lshl_add_u64 v[210:211], s[30:31], 0, v[132:133]
	s_mov_b32 m0, s45
	s_nop 0
	global_load_lds_dwordx4 v[210:211], off
	s_setprio 1
	s_waitcnt vmcnt(8) lgkmcnt(0)
	s_barrier
	v_mfma_f32_16x16x32_bf16 v[2:5], v[26:29], v[202:205], v[2:5]
	v_mfma_f32_16x16x32_bf16 v[6:9], v[114:117], v[202:205], v[6:9]
	v_mfma_f32_16x16x32_bf16 v[146:149], v[26:29], v[178:181], v[146:149]
	v_mfma_f32_16x16x32_bf16 v[150:153], v[114:117], v[178:181], v[150:153]
	v_mfma_f32_16x16x32_bf16 v[154:157], v[26:29], v[186:189], v[154:157]
	v_mfma_f32_16x16x32_bf16 v[158:161], v[114:117], v[186:189], v[158:161]
	v_mfma_f32_16x16x32_bf16 v[162:165], v[26:29], v[194:197], v[162:165]
	v_mfma_f32_16x16x32_bf16 v[166:169], v[114:117], v[194:197], v[166:169]
	v_mfma_f32_16x16x32_bf16 v[2:5], v[30:33], v[206:209], v[2:5]
	v_mfma_f32_16x16x32_bf16 v[6:9], v[118:121], v[206:209], v[6:9]
	v_mfma_f32_16x16x32_bf16 v[146:149], v[30:33], v[182:185], v[146:149]
	v_mfma_f32_16x16x32_bf16 v[150:153], v[118:121], v[182:185], v[150:153]
	v_mfma_f32_16x16x32_bf16 v[154:157], v[30:33], v[190:193], v[154:157]
	v_mfma_f32_16x16x32_bf16 v[158:161], v[118:121], v[190:193], v[158:161]
	v_mfma_f32_16x16x32_bf16 v[162:165], v[30:33], v[198:201], v[162:165]
	v_mfma_f32_16x16x32_bf16 v[166:169], v[118:121], v[198:201], v[166:169]
	v_mfma_f32_16x16x32_bf16 v[10:13], v[122:125], v[178:181], v[10:13]
	v_mfma_f32_16x16x32_bf16 v[14:17], v[170:173], v[178:181], v[14:17]
	v_mfma_f32_16x16x32_bf16 v[26:29], v[122:125], v[186:189], v[62:65]
	v_mfma_f32_16x16x32_bf16 v[30:33], v[170:173], v[186:189], v[102:105]
	v_mfma_f32_16x16x32_bf16 v[62:65], v[122:125], v[194:197], v[106:109]
	v_mfma_f32_16x16x32_bf16 v[102:105], v[170:173], v[194:197], v[110:113]
	v_mfma_f32_16x16x32_bf16 v[18:21], v[122:125], v[202:205], v[18:21]
	v_mfma_f32_16x16x32_bf16 v[22:25], v[170:173], v[202:205], v[22:25]
	v_mfma_f32_16x16x32_bf16 v[10:13], v[126:129], v[182:185], v[10:13]
	v_mfma_f32_16x16x32_bf16 v[14:17], v[174:177], v[182:185], v[14:17]
	v_mfma_f32_16x16x32_bf16 v[26:29], v[126:129], v[190:193], v[26:29]
	v_mfma_f32_16x16x32_bf16 v[30:33], v[174:177], v[190:193], v[30:33]
	v_mfma_f32_16x16x32_bf16 v[62:65], v[126:129], v[198:201], v[62:65]
	v_mfma_f32_16x16x32_bf16 v[102:105], v[174:177], v[198:201], v[102:105]
	v_mfma_f32_16x16x32_bf16 v[18:21], v[126:129], v[206:209], v[18:21]
	v_mfma_f32_16x16x32_bf16 v[22:25], v[174:177], v[206:209], v[22:25]
	s_barrier
	s_setprio 0
	ds_read_b128 v[106:109], v142
	ds_read_b128 v[110:113], v142 offset:1024
	ds_read_b128 v[114:117], v142 offset:2048
	ds_read_b128 v[118:121], v142 offset:3072
	ds_read_b128 v[122:125], v143
	ds_read_b128 v[126:129], v143 offset:1024
	ds_read_b128 v[170:173], v143 offset:2048
	ds_read_b128 v[174:177], v143 offset:3072
	s_add_u32 s22, s22, 0x11800
	s_addc_u32 s23, s23, 0
	s_mov_b32 m0, s50
	v_lshl_add_u64 v[210:211], s[22:23], 0, v[130:131]
	ds_read_b128 v[178:181], v144
	ds_read_b128 v[182:185], v144 offset:1024
	ds_read_b128 v[186:189], v144 offset:2048
	ds_read_b128 v[190:193], v144 offset:3072
	ds_read_b128 v[194:197], v144 offset:4096
	ds_read_b128 v[198:201], v144 offset:5120
	ds_read_b128 v[202:205], v144 offset:6144
	ds_read_b128 v[206:209], v144 offset:7168
	global_load_lds_dwordx4 v[210:211], off
	v_lshl_add_u64 v[210:211], s[22:23], 0, v[132:133]
	s_mov_b32 m0, s51
	s_nop 0
	global_load_lds_dwordx4 v[210:211], off
	s_setprio 1
	s_waitcnt vmcnt(8) lgkmcnt(0)
	s_barrier
; #define PG8_STAGE(bufoff, gbase, voff) do { _Pragma("unroll") for (int _i = 0; _i < 2; ++_i) \
;         __builtin_amdgcn_global_load_lds((const unsigned*)((const char*)(gbase) + (voff)[_i]), (PG8_LAS unsigned*)(lds + (bufoff) + ldsw + _i * 8192), 16, 0, 0); } while (0)
; #define PG8_LDA(dst, b, h) do { _Pragma("unroll") for (int m = 0; m < 4; ++m) _Pragma("unroll") for (int k = 0; k < 2; ++k) dst[m][k] = *(const PG8_LAS bf16x8*)(lds + PG8_SA(b, h) + aoff + m * 2048 + k * 1024); } while (0)
; #define PG8_LDB(dst, b, h) do { _Pragma("unroll") for (int n = 0; n < 2; ++n) _Pragma("unroll") for (int k = 0; k < 2; ++k) dst[n][k] = *(const PG8_LAS bf16x8*)(lds + PG8_SB(b, h) + boff + n * 2048 + k * 1024); } while (0)
; #define PG8_MMA(ai, bj, At, Bt) do { __builtin_amdgcn_s_setprio(1); _Pragma("unroll") for (int m = 0; m < 4; ++m) _Pragma("unroll") for (int n = 0; n < 2; ++n) _Pragma("unroll") for (int k = 0; k < 2; ++k) \
;         acc[ai][bj][m][n] = __builtin_amdgcn_mfma_f32_16x16x32_bf16(Bt[n][k], At[m][k], acc[ai][bj][m][n], 0, 0, 0); __builtin_amdgcn_s_setprio(0); } while (0)
; #define PG8_WAIT_V(n) asm volatile("s_waitcnt vmcnt(" #n ")" ::: "memory")
; #define PG8_WAIT_L(n) asm volatile("s_waitcnt lgkmcnt(" #n ")" ::: "memory")
; #define PG8_BAR __builtin_amdgcn_s_barrier()
; #define PG8_SCHED __builtin_amdgcn_sched_barrier(0)
; template <class Epi, class Sched, bool ALIGN_EPI, int LMASK = -1, int LMASKB = LMASK>
; __device__ __forceinline__ void gemm_phase(PG8_LAS unsigned char* lds, const Gemm g, const Sched& S, const Epi& E) {
;     ...
;             PG8_LDB(B0, 0, 0); PG8_LDB(B1, 0, 1); PG8_SCHED; PG8_LDA(At, 0, 0); PG8_STAGE(PG8_SA(1, 1), a1 + hstepA, voffA);
;             PG8_WAIT_V(8); PG8_WAIT_L(0); PG8_BAR; PG8_MMA(0, 0, At, B0); PG8_MMA(0, 1, At, B1); PG8_BAR; PG8_SCHED;
;             PG8_LDA(At, 0, 1); PG8_STAGE(PG8_SB(0, 0), b2, voffB); PG8_STAGE(PG8_SB(0, 1), b2 + hstepB, voffB); PG8_STAGE(PG8_SA(0, 0), a2, voffA);
;             PG8_WAIT_V(8); PG8_WAIT_L(0); PG8_BAR; PG8_MMA(1, 0, At, B0); PG8_MMA(1, 1, At, B1); PG8_BAR; PG8_SCHED;
	v_mfma_f32_16x16x32_bf16 v[66:69], v[106:109], v[178:181], v[66:69]
	v_mfma_f32_16x16x32_bf16 v[70:73], v[114:117], v[178:181], v[70:73]
	v_mfma_f32_16x16x32_bf16 v[74:77], v[106:109], v[186:189], v[74:77]
	v_mfma_f32_16x16x32_bf16 v[78:81], v[114:117], v[186:189], v[78:81]
	v_mfma_f32_16x16x32_bf16 v[82:85], v[106:109], v[194:197], v[82:85]
	v_mfma_f32_16x16x32_bf16 v[86:89], v[114:117], v[194:197], v[86:89]
	v_mfma_f32_16x16x32_bf16 v[90:93], v[106:109], v[202:205], v[90:93]
	v_mfma_f32_16x16x32_bf16 v[94:97], v[114:117], v[202:205], v[94:97]
	v_mfma_f32_16x16x32_bf16 v[66:69], v[110:113], v[182:185], v[66:69]
	v_mfma_f32_16x16x32_bf16 v[70:73], v[118:121], v[182:185], v[70:73]
	v_mfma_f32_16x16x32_bf16 v[74:77], v[110:113], v[190:193], v[74:77]
	v_mfma_f32_16x16x32_bf16 v[78:81], v[118:121], v[190:193], v[78:81]
	v_mfma_f32_16x16x32_bf16 v[82:85], v[110:113], v[198:201], v[82:85]
	v_mfma_f32_16x16x32_bf16 v[86:89], v[118:121], v[198:201], v[86:89]
	v_mfma_f32_16x16x32_bf16 v[90:93], v[110:113], v[206:209], v[90:93]
	v_mfma_f32_16x16x32_bf16 v[94:97], v[118:121], v[206:209], v[94:97]
	v_mfma_f32_16x16x32_bf16 v[34:37], v[170:173], v[178:181], v[34:37]
	v_mfma_f32_16x16x32_bf16 v[98:101], v[122:125], v[178:181], v[98:101]
	v_mfma_f32_16x16x32_bf16 v[178:181], v[174:177], v[182:185], v[34:37]
	v_mfma_f32_16x16x32_bf16 v[34:37], v[122:125], v[186:189], v[38:41]
	v_mfma_f32_16x16x32_bf16 v[210:213], v[126:129], v[182:185], v[98:101]
	v_mfma_f32_16x16x32_bf16 v[182:185], v[126:129], v[190:193], v[34:37]
	v_mfma_f32_16x16x32_bf16 v[34:37], v[170:173], v[186:189], v[42:45]
	v_mfma_f32_16x16x32_bf16 v[42:45], v[174:177], v[190:193], v[34:37]
	v_mfma_f32_16x16x32_bf16 v[34:37], v[122:125], v[194:197], v[46:49]
	v_mfma_f32_16x16x32_bf16 v[46:49], v[126:129], v[198:201], v[34:37]
	v_mfma_f32_16x16x32_bf16 v[34:37], v[170:173], v[194:197], v[50:53]
	v_mfma_f32_16x16x32_bf16 v[50:53], v[174:177], v[198:201], v[34:37]
	v_mfma_f32_16x16x32_bf16 v[34:37], v[122:125], v[202:205], v[54:57]
	v_mfma_f32_16x16x32_bf16 v[54:57], v[126:129], v[206:209], v[34:37]
	v_mfma_f32_16x16x32_bf16 v[34:37], v[170:173], v[202:205], v[58:61]
	v_mfma_f32_16x16x32_bf16 v[58:61], v[174:177], v[206:209], v[34:37]
	s_barrier
	s_setprio 0
	s_mov_b32 m0, s52
	v_lshl_add_u64 v[246:247], s[26:27], 0, v[130:131]
	s_add_u32 s22, s26, 0x10000
	s_nop 1
	ds_read_b128 v[34:37], v144 offset:16384
	ds_read_b128 v[38:41], v144 offset:17408
	ds_read_b128 v[98:101], v144 offset:18432
	ds_read_b128 v[186:189], v144 offset:19456
	ds_read_b128 v[190:193], v144 offset:20480
	ds_read_b128 v[194:197], v144 offset:21504
	ds_read_b128 v[198:201], v144 offset:22528
	ds_read_b128 v[202:205], v144 offset:23552
	global_load_lds_dwordx4 v[246:247], off
	v_lshl_add_u64 v[248:249], s[26:27], 0, v[132:133]
	s_mov_b32 m0, s15
	s_addc_u32 s23, s27, 0
	global_load_lds_dwordx4 v[248:249], off
	v_lshl_add_u64 v[206:207], s[22:23], 0, v[130:131]
	s_mov_b32 m0, s17
	v_lshl_add_u64 v[250:251], s[28:29], 0, v[130:131]
	global_load_lds_dwordx4 v[206:207], off
	v_lshl_add_u64 v[206:207], s[22:23], 0, v[132:133]
	s_mov_b32 m0, s54
	v_lshl_add_u64 v[252:253], s[28:29], 0, v[132:133]
	global_load_lds_dwordx4 v[206:207], off
	s_mov_b32 m0, s19
	s_nop 0
	global_load_lds_dwordx4 v[250:251], off
	s_mov_b32 m0, s39
	s_nop 0
	global_load_lds_dwordx4 v[252:253], off
	s_setprio 1
	s_waitcnt vmcnt(8) lgkmcnt(0)
	s_barrier
	v_mfma_f32_16x16x32_bf16 v[2:5], v[106:109], v[198:201], v[2:5]
	v_mfma_f32_16x16x32_bf16 v[6:9], v[114:117], v[198:201], v[6:9]
	v_mfma_f32_16x16x32_bf16 v[146:149], v[106:109], v[34:37], v[146:149]
	v_mfma_f32_16x16x32_bf16 v[150:153], v[114:117], v[34:37], v[150:153]
	v_mfma_f32_16x16x32_bf16 v[154:157], v[106:109], v[98:101], v[154:157]
	v_mfma_f32_16x16x32_bf16 v[158:161], v[114:117], v[98:101], v[158:161]
	v_mfma_f32_16x16x32_bf16 v[162:165], v[106:109], v[190:193], v[162:165]
	v_mfma_f32_16x16x32_bf16 v[166:169], v[114:117], v[190:193], v[166:169]
	v_mfma_f32_16x16x32_bf16 v[2:5], v[110:113], v[202:205], v[2:5]
	v_mfma_f32_16x16x32_bf16 v[6:9], v[118:121], v[202:205], v[6:9]
	v_mfma_f32_16x16x32_bf16 v[146:149], v[110:113], v[38:41], v[146:149]
	v_mfma_f32_16x16x32_bf16 v[150:153], v[118:121], v[38:41], v[150:153]
	v_mfma_f32_16x16x32_bf16 v[154:157], v[110:113], v[186:189], v[154:157]
	v_mfma_f32_16x16x32_bf16 v[158:161], v[118:121], v[186:189], v[158:161]
	v_mfma_f32_16x16x32_bf16 v[162:165], v[110:113], v[194:197], v[162:165]
	v_mfma_f32_16x16x32_bf16 v[166:169], v[118:121], v[194:197], v[166:169]
	v_mfma_f32_16x16x32_bf16 v[10:13], v[122:125], v[34:37], v[10:13]
	v_mfma_f32_16x16x32_bf16 v[14:17], v[170:173], v[34:37], v[14:17]
	v_mfma_f32_16x16x32_bf16 v[26:29], v[122:125], v[98:101], v[26:29]
	v_mfma_f32_16x16x32_bf16 v[30:33], v[170:173], v[98:101], v[30:33]
	v_mfma_f32_16x16x32_bf16 v[34:37], v[122:125], v[190:193], v[62:65]
	v_mfma_f32_16x16x32_bf16 v[26:29], v[126:129], v[186:189], v[26:29]
	v_mfma_f32_16x16x32_bf16 v[30:33], v[174:177], v[186:189], v[30:33]
	v_mfma_f32_16x16x32_bf16 v[186:189], v[126:129], v[194:197], v[34:37]
	v_mfma_f32_16x16x32_bf16 v[34:37], v[170:173], v[190:193], v[102:105]
	v_mfma_f32_16x16x32_bf16 v[18:21], v[122:125], v[198:201], v[18:21]
	v_mfma_f32_16x16x32_bf16 v[10:13], v[126:129], v[38:41], v[10:13]
	v_mfma_f32_16x16x32_bf16 v[14:17], v[174:177], v[38:41], v[14:17]
	v_mfma_f32_16x16x32_bf16 v[190:193], v[174:177], v[194:197], v[34:37]
	v_mfma_f32_16x16x32_bf16 v[194:197], v[126:129], v[202:205], v[18:21]
	v_mfma_f32_16x16x32_bf16 v[18:21], v[170:173], v[198:201], v[22:25]
	v_mfma_f32_16x16x32_bf16 v[170:173], v[174:177], v[202:205], v[18:21]
	s_barrier
; #define PG8_STAGE(bufoff, gbase, voff) do { _Pragma("unroll") for (int _i = 0; _i < 2; ++_i) \
;         __builtin_amdgcn_global_load_lds((const unsigned*)((const char*)(gbase) + (voff)[_i]), (PG8_LAS unsigned*)(lds + (bufoff) + ldsw + _i * 8192), 16, 0, 0); } while (0)
; #define PG8_LDA(dst, b, h) do { _Pragma("unroll") for (int m = 0; m < 4; ++m) _Pragma("unroll") for (int k = 0; k < 2; ++k) dst[m][k] = *(const PG8_LAS bf16x8*)(lds + PG8_SA(b, h) + aoff + m * 2048 + k * 1024); } while (0)
; #define PG8_LDB(dst, b, h) do { _Pragma("unroll") for (int n = 0; n < 2; ++n) _Pragma("unroll") for (int k = 0; k < 2; ++k) dst[n][k] = *(const PG8_LAS bf16x8*)(lds + PG8_SB(b, h) + boff + n * 2048 + k * 1024); } while (0)
; #define PG8_MMA(ai, bj, At, Bt) do { __builtin_amdgcn_s_setprio(1); _Pragma("unroll") for (int m = 0; m < 4; ++m) _Pragma("unroll") for (int n = 0; n < 2; ++n) _Pragma("unroll") for (int k = 0; k < 2; ++k) \
;         acc[ai][bj][m][n] = __builtin_amdgcn_mfma_f32_16x16x32_bf16(Bt[n][k], At[m][k], acc[ai][bj][m][n], 0, 0, 0); __builtin_amdgcn_s_setprio(0); } while (0)
; #define PG8_WAIT_V(n) asm volatile("s_waitcnt vmcnt(" #n ")" ::: "memory")
; #define PG8_WAIT_L(n) asm volatile("s_waitcnt lgkmcnt(" #n ")" ::: "memory")
; #define PG8_BAR __builtin_amdgcn_s_barrier()
; #define PG8_SCHED __builtin_amdgcn_sched_barrier(0)
; template <class Epi, class Sched, bool ALIGN_EPI, int LMASK = -1, int LMASKB = LMASK>
; __device__ __forceinline__ void gemm_phase(PG8_LAS unsigned char* lds, const Gemm g, const Sched& S, const Epi& E) {
;     ...
;             PG8_LDB(B0, 1, 0); PG8_LDB(B1, 1, 1); PG8_SCHED; PG8_LDA(At, 1, 0); PG8_STAGE(PG8_SA(0, 1), a2 + hstepA, voffA);
;             PG8_WAIT_V(8); PG8_WAIT_L(0); PG8_BAR; PG8_MMA(0, 0, At, B0); PG8_MMA(0, 1, At, B1); PG8_BAR; PG8_SCHED;
;             PG8_LDA(At, 1, 1); PG8_STAGE(PG8_SB(1, 0), b3, voffB); PG8_STAGE(PG8_SB(1, 1), b3 + hstepB, voffB); PG8_STAGE(PG8_SA(1, 0), a3, voffA);
;             PG8_WAIT_V(8); PG8_WAIT_L(0); PG8_BAR; PG8_MMA(1, 0, At, B0); PG8_MMA(1, 1, At, B1); PG8_BAR; PG8_SCHED;
;         }
;         if constexpr (ALIGN_EPI) { if (wr == 0) PG8_BAR; }
	s_setprio 0
	ds_read_b128 v[62:65], v134
	ds_read_b128 v[174:177], v134 offset:1024
	ds_read_b128 v[198:201], v134 offset:2048
	ds_read_b128 v[202:205], v134 offset:3072
	ds_read_b128 v[206:209], v222
	ds_read_b128 v[214:217], v222 offset:1024
	ds_read_b128 v[218:221], v222 offset:2048
	ds_read_b128 v[222:225], v222 offset:3072
	s_add_u32 s22, s28, 0x10000
	s_addc_u32 s23, s29, 0
	s_mov_b32 m0, s40
	v_lshl_add_u64 v[34:35], s[22:23], 0, v[130:131]
	ds_read_b128 v[18:21], v144 offset:32768
	ds_read_b128 v[22:25], v144 offset:33792
	ds_read_b128 v[110:113], v144 offset:34816
	ds_read_b128 v[226:229], v144 offset:35840
	ds_read_b128 v[230:233], v144 offset:36864
	ds_read_b128 v[234:237], v144 offset:37888
	ds_read_b128 v[238:241], v144 offset:38912
	ds_read_b128 v[242:245], v144 offset:39936
	global_load_lds_dwordx4 v[34:35], off
	v_lshl_add_u64 v[34:35], s[22:23], 0, v[132:133]
	s_mov_b32 m0, s41
	s_nop 0
	global_load_lds_dwordx4 v[34:35], off
	s_setprio 1
	s_waitcnt vmcnt(8) lgkmcnt(0)
	s_barrier
	v_mfma_f32_16x16x32_bf16 v[34:37], v[62:65], v[18:21], v[66:69]
	v_mfma_f32_16x16x32_bf16 v[114:117], v[174:177], v[22:25], v[34:37]
	v_mfma_f32_16x16x32_bf16 v[34:37], v[198:201], v[18:21], v[70:73]
	v_mfma_f32_16x16x32_bf16 v[118:121], v[202:205], v[22:25], v[34:37]
	v_mfma_f32_16x16x32_bf16 v[34:37], v[62:65], v[110:113], v[74:77]
	v_mfma_f32_16x16x32_bf16 v[98:101], v[174:177], v[226:229], v[34:37]
	v_mfma_f32_16x16x32_bf16 v[34:37], v[198:201], v[110:113], v[78:81]
	v_mfma_f32_16x16x32_bf16 v[102:105], v[202:205], v[226:229], v[34:37]
	v_mfma_f32_16x16x32_bf16 v[34:37], v[62:65], v[230:233], v[82:85]
	v_mfma_f32_16x16x32_bf16 v[66:69], v[174:177], v[234:237], v[34:37]
	v_mfma_f32_16x16x32_bf16 v[34:37], v[198:201], v[230:233], v[86:89]
	v_mfma_f32_16x16x32_bf16 v[70:73], v[202:205], v[234:237], v[34:37]
	v_mfma_f32_16x16x32_bf16 v[34:37], v[62:65], v[238:241], v[90:93]
	v_mfma_f32_16x16x32_bf16 v[38:41], v[198:201], v[238:241], v[94:97]
	v_mfma_f32_16x16x32_bf16 v[34:37], v[174:177], v[242:245], v[34:37]
	v_mfma_f32_16x16x32_bf16 v[38:41], v[202:205], v[242:245], v[38:41]
	v_mfma_f32_16x16x32_bf16 v[74:77], v[206:209], v[18:21], v[210:213]
	v_mfma_f32_16x16x32_bf16 v[18:21], v[218:221], v[18:21], v[178:181]
	v_mfma_f32_16x16x32_bf16 v[126:129], v[222:225], v[22:25], v[18:21]
	v_mfma_f32_16x16x32_bf16 v[18:21], v[206:209], v[110:113], v[182:185]
	v_mfma_f32_16x16x32_bf16 v[106:109], v[214:217], v[226:229], v[18:21]
	v_mfma_f32_16x16x32_bf16 v[18:21], v[218:221], v[110:113], v[42:45]
	v_mfma_f32_16x16x32_bf16 v[110:113], v[222:225], v[226:229], v[18:21]
	v_mfma_f32_16x16x32_bf16 v[18:21], v[206:209], v[230:233], v[46:49]
	v_mfma_f32_16x16x32_bf16 v[122:125], v[214:217], v[22:25], v[74:77]
	v_mfma_f32_16x16x32_bf16 v[74:77], v[214:217], v[234:237], v[18:21]
	v_mfma_f32_16x16x32_bf16 v[18:21], v[218:221], v[230:233], v[50:53]
	v_mfma_f32_16x16x32_bf16 v[78:81], v[222:225], v[234:237], v[18:21]
	v_mfma_f32_16x16x32_bf16 v[18:21], v[206:209], v[238:241], v[54:57]
	v_mfma_f32_16x16x32_bf16 v[42:45], v[214:217], v[242:245], v[18:21]
	v_mfma_f32_16x16x32_bf16 v[18:21], v[218:221], v[238:241], v[58:61]
	v_mfma_f32_16x16x32_bf16 v[46:49], v[222:225], v[242:245], v[18:21]
	s_barrier
	s_setprio 0
	s_mov_b32 m0, s35
	s_nop 3
	v_lshl_add_u64 v[18:19], v[246:247], 0, s[8:9]
	s_add_u32 s22, s26, 0x10800
	ds_read_b128 v[58:61], v144 offset:49152
	ds_read_b128 v[94:97], v144 offset:50176
	ds_read_b128 v[178:181], v144 offset:51200
	ds_read_b128 v[182:185], v144 offset:52224
	ds_read_b128 v[210:213], v144 offset:53248
	ds_read_b128 v[226:229], v144 offset:54272
	ds_read_b128 v[230:233], v144 offset:55296
	ds_read_b128 v[234:237], v144 offset:56320
	global_load_lds_dwordx4 v[18:19], off
	v_lshl_add_u64 v[18:19], v[248:249], 0, s[8:9]
	s_mov_b32 m0, s34
	s_addc_u32 s23, s27, 0
	global_load_lds_dwordx4 v[18:19], off
	v_lshl_add_u64 v[18:19], s[22:23], 0, v[130:131]
	s_mov_b32 m0, s24
	s_nop 0
	global_load_lds_dwordx4 v[18:19], off
	v_lshl_add_u64 v[18:19], s[22:23], 0, v[132:133]
	s_mov_b32 m0, s25
	s_nop 0
	global_load_lds_dwordx4 v[18:19], off
	v_lshl_add_u64 v[18:19], v[250:251], 0, s[8:9]
	s_mov_b32 m0, s44
	s_nop 0
	global_load_lds_dwordx4 v[18:19], off
	v_lshl_add_u64 v[18:19], v[252:253], 0, s[8:9]
	s_mov_b32 m0, s45
	s_nop 0
	global_load_lds_dwordx4 v[18:19], off
	s_setprio 1
	s_waitcnt vmcnt(8) lgkmcnt(0)
	s_barrier
	v_mfma_f32_16x16x32_bf16 v[18:21], v[62:65], v[58:61], v[146:149]
	v_mfma_f32_16x16x32_bf16 v[82:85], v[174:177], v[94:97], v[18:21]
	v_mfma_f32_16x16x32_bf16 v[18:21], v[198:201], v[58:61], v[150:153]
	v_mfma_f32_16x16x32_bf16 v[86:89], v[202:205], v[94:97], v[18:21]
	v_mfma_f32_16x16x32_bf16 v[18:21], v[62:65], v[178:181], v[154:157]
	v_mfma_f32_16x16x32_bf16 v[50:53], v[174:177], v[182:185], v[18:21]
	v_mfma_f32_16x16x32_bf16 v[18:21], v[198:201], v[178:181], v[158:161]
	v_mfma_f32_16x16x32_bf16 v[54:57], v[202:205], v[182:185], v[18:21]
	v_mfma_f32_16x16x32_bf16 v[18:21], v[62:65], v[210:213], v[162:165]
	v_mfma_f32_16x16x32_bf16 v[22:25], v[198:201], v[210:213], v[166:169]
	v_mfma_f32_16x16x32_bf16 v[2:5], v[62:65], v[230:233], v[2:5]
	v_mfma_f32_16x16x32_bf16 v[6:9], v[198:201], v[230:233], v[6:9]
	v_mfma_f32_16x16x32_bf16 v[18:21], v[174:177], v[226:229], v[18:21]
	v_mfma_f32_16x16x32_bf16 v[22:25], v[202:205], v[226:229], v[22:25]
	v_mfma_f32_16x16x32_bf16 v[2:5], v[174:177], v[234:237], v[2:5]
	v_mfma_f32_16x16x32_bf16 v[6:9], v[202:205], v[234:237], v[6:9]
	v_mfma_f32_16x16x32_bf16 v[10:13], v[206:209], v[58:61], v[10:13]
	v_mfma_f32_16x16x32_bf16 v[90:93], v[214:217], v[94:97], v[10:13]
	v_mfma_f32_16x16x32_bf16 v[10:13], v[218:221], v[58:61], v[14:17]
	v_mfma_f32_16x16x32_bf16 v[94:97], v[222:225], v[94:97], v[10:13]
	v_mfma_f32_16x16x32_bf16 v[10:13], v[206:209], v[178:181], v[26:29]
	v_mfma_f32_16x16x32_bf16 v[58:61], v[214:217], v[182:185], v[10:13]
	v_mfma_f32_16x16x32_bf16 v[10:13], v[218:221], v[178:181], v[30:33]
	v_mfma_f32_16x16x32_bf16 v[62:65], v[222:225], v[182:185], v[10:13]
	v_mfma_f32_16x16x32_bf16 v[10:13], v[206:209], v[210:213], v[186:189]
	v_mfma_f32_16x16x32_bf16 v[26:29], v[214:217], v[226:229], v[10:13]
	v_mfma_f32_16x16x32_bf16 v[10:13], v[218:221], v[210:213], v[190:193]
	v_mfma_f32_16x16x32_bf16 v[30:33], v[222:225], v[226:229], v[10:13]
	v_mfma_f32_16x16x32_bf16 v[10:13], v[206:209], v[230:233], v[194:197]
	v_mfma_f32_16x16x32_bf16 v[14:17], v[218:221], v[230:233], v[170:173]
	v_mfma_f32_16x16x32_bf16 v[10:13], v[214:217], v[234:237], v[10:13]
	v_mfma_f32_16x16x32_bf16 v[14:17], v[222:225], v[234:237], v[14:17]
	s_barrier
	s_setprio 0
	s_andn2_b64 vcc, exec, s[10:11]
	s_cbranch_vccnz .LBB0_208
	s_barrier

; #define PG8_STAGE(bufoff, gbase, voff) do { _Pragma("unroll") for (int _i = 0; _i < 2; ++_i) \
;         __builtin_amdgcn_global_load_lds((const unsigned*)((const char*)(gbase) + (voff)[_i]), (PG8_LAS unsigned*)(lds + (bufoff) + ldsw + _i * 8192), 16, 0, 0); } while (0)
; #define PG8_LDA(dst, b, h) do { _Pragma("unroll") for (int m = 0; m < 4; ++m) _Pragma("unroll") for (int k = 0; k < 2; ++k) dst[m][k] = *(const PG8_LAS bf16x8*)(lds + PG8_SA(b, h) + aoff + m * 2048 + k * 1024); } while (0)
; #define PG8_LDB(dst, b, h) do { _Pragma("unroll") for (int n = 0; n < 2; ++n) _Pragma("unroll") for (int k = 0; k < 2; ++k) dst[n][k] = *(const PG8_LAS bf16x8*)(lds + PG8_SB(b, h) + boff + n * 2048 + k * 1024); } while (0)
; #define PG8_MMA(ai, bj, At, Bt) do { __builtin_amdgcn_s_setprio(1); _Pragma("unroll") for (int m = 0; m < 4; ++m) _Pragma("unroll") for (int n = 0; n < 2; ++n) _Pragma("unroll") for (int k = 0; k < 2; ++k) \
;         acc[ai][bj][m][n] = __builtin_amdgcn_mfma_f32_16x16x32_bf16(Bt[n][k], At[m][k], acc[ai][bj][m][n], 0, 0, 0); __builtin_amdgcn_s_setprio(0); } while (0)
; #define PG8_WAIT_V(n) asm volatile("s_waitcnt vmcnt(" #n ")" ::: "memory")
; #define PG8_WAIT_L(n) asm volatile("s_waitcnt lgkmcnt(" #n ")" ::: "memory")
; #define PG8_BAR __builtin_amdgcn_s_barrier()
; #define PG8_SCHED __builtin_amdgcn_sched_barrier(0)
; template <class Epi, class Sched, bool ALIGN_EPI, int LMASK = -1, int LMASKB = LMASK>
; __device__ __forceinline__ void gemm_phase(PG8_LAS unsigned char* lds, const Gemm g, const Sched& S, const Epi& E) {
;     ...
;             PG8_LDB(B0, 0, 0); PG8_LDB(B1, 0, 1); PG8_SCHED; PG8_LDA(At, 0, 0); PG8_STAGE(PG8_SA(1, 1), a1 + hstepA, voffA);
;             PG8_WAIT_V(8); PG8_WAIT_L(0); PG8_BAR; PG8_MMA(0, 0, At, B0); PG8_MMA(0, 1, At, B1); PG8_BAR; PG8_SCHED;
;             PG8_LDA(At, 0, 1); PG8_STAGE(PG8_SB(0, 0), b2, voffB); PG8_STAGE(PG8_SB(0, 1), b2 + hstepB, voffB); PG8_STAGE(PG8_SA(0, 0), a2, voffA);
;             PG8_WAIT_V(8); PG8_WAIT_L(0); PG8_BAR; PG8_MMA(1, 0, At, B0); PG8_MMA(1, 1, At, B1); PG8_BAR; PG8_SCHED;
.LBB0_284:
	s_add_u32 s10, s8, 0xfff00800
	s_addc_u32 s11, s9, -1
	s_add_i32 s55, 0, 0x10000
	s_cmp_eq_u32 s54, 60
	s_cselect_b32 s37, s0, s11
	s_cselect_b32 s36, s1, s10
	s_cselect_b32 s11, s2, s29
	s_cselect_b32 s10, s7, s27
	s_add_i32 s58, 0, 0x14000
	v_add_u32_e32 v142, s55, v161
	v_add_u32_e32 v154, s58, v161
	ds_read_b128 v[130:133], v142
	ds_read_b128 v[134:137], v142 offset:1024
	ds_read_b128 v[138:141], v142 offset:2048
	ds_read_b128 v[142:145], v142 offset:3072
	ds_read_b128 v[172:175], v154
	ds_read_b128 v[188:191], v154 offset:1024
	ds_read_b128 v[218:221], v154 offset:2048
	ds_read_b128 v[222:225], v154 offset:3072
	v_lshl_add_u64 v[154:155], s[8:9], 0, v[150:151]
	s_add_i32 m0, s45, 0xc000
	ds_read_b128 v[226:229], v171
	ds_read_b128 v[230:233], v171 offset:1024
	ds_read_b128 v[234:237], v171 offset:2048
	ds_read_b128 v[238:241], v171 offset:3072
	ds_read_b128 v[242:245], v171 offset:4096
	ds_read_b128 v[246:249], v171 offset:5120
	ds_read_b128 v[250:253], v171 offset:6144
	ds_read_b128 v[206:209], v171 offset:7168
	global_load_lds_dwordx4 v[154:155], off
	v_lshl_add_u64 v[154:155], s[8:9], 0, v[152:153]
	s_add_i32 m0, s45, 0xe000
	s_nop 0
	global_load_lds_dwordx4 v[154:155], off
	s_setprio 1
	s_waitcnt vmcnt(8) lgkmcnt(0)
	s_barrier
	v_mfma_f32_16x16x32_bf16 v[126:129], v[130:133], v[226:229], v[126:129]
	v_mfma_f32_16x16x32_bf16 v[122:125], v[138:141], v[226:229], v[122:125]
	v_mfma_f32_16x16x32_bf16 v[118:121], v[130:133], v[234:237], v[118:121]
	v_mfma_f32_16x16x32_bf16 v[110:113], v[138:141], v[234:237], v[110:113]
	v_mfma_f32_16x16x32_bf16 v[102:105], v[130:133], v[242:245], v[102:105]
	v_mfma_f32_16x16x32_bf16 v[94:97], v[138:141], v[242:245], v[94:97]
	v_mfma_f32_16x16x32_bf16 v[86:89], v[130:133], v[250:253], v[86:89]
	v_mfma_f32_16x16x32_bf16 v[78:81], v[138:141], v[250:253], v[78:81]
	v_mfma_f32_16x16x32_bf16 v[126:129], v[134:137], v[230:233], v[126:129]
	v_mfma_f32_16x16x32_bf16 v[122:125], v[142:145], v[230:233], v[122:125]
	v_mfma_f32_16x16x32_bf16 v[118:121], v[134:137], v[238:241], v[118:121]
	v_mfma_f32_16x16x32_bf16 v[110:113], v[142:145], v[238:241], v[110:113]
	v_mfma_f32_16x16x32_bf16 v[102:105], v[134:137], v[246:249], v[102:105]
	v_mfma_f32_16x16x32_bf16 v[94:97], v[142:145], v[246:249], v[94:97]
	v_mfma_f32_16x16x32_bf16 v[86:89], v[134:137], v[206:209], v[86:89]
	v_mfma_f32_16x16x32_bf16 v[78:81], v[142:145], v[206:209], v[78:81]
	v_mfma_f32_16x16x32_bf16 v[114:117], v[172:175], v[226:229], v[114:117]
	v_mfma_f32_16x16x32_bf16 v[106:109], v[218:221], v[226:229], v[106:109]
	v_mfma_f32_16x16x32_bf16 v[98:101], v[172:175], v[234:237], v[98:101]
	v_mfma_f32_16x16x32_bf16 v[90:93], v[218:221], v[234:237], v[90:93]
	v_mfma_f32_16x16x32_bf16 v[82:85], v[172:175], v[242:245], v[82:85]
	v_mfma_f32_16x16x32_bf16 v[74:77], v[218:221], v[242:245], v[74:77]
	v_mfma_f32_16x16x32_bf16 v[70:73], v[172:175], v[250:253], v[70:73]
	v_mfma_f32_16x16x32_bf16 v[66:69], v[218:221], v[250:253], v[66:69]
	v_mfma_f32_16x16x32_bf16 v[114:117], v[188:191], v[230:233], v[114:117]
	v_mfma_f32_16x16x32_bf16 v[106:109], v[222:225], v[230:233], v[106:109]
	v_mfma_f32_16x16x32_bf16 v[98:101], v[188:191], v[238:241], v[98:101]
	v_mfma_f32_16x16x32_bf16 v[90:93], v[222:225], v[238:241], v[90:93]
	v_mfma_f32_16x16x32_bf16 v[82:85], v[188:191], v[246:249], v[82:85]
	v_mfma_f32_16x16x32_bf16 v[74:77], v[222:225], v[246:249], v[74:77]
	v_mfma_f32_16x16x32_bf16 v[70:73], v[188:191], v[206:209], v[70:73]
	v_mfma_f32_16x16x32_bf16 v[66:69], v[222:225], v[206:209], v[66:69]
	s_barrier
	s_setprio 0
	s_add_i32 s55, s55, s43
	v_lshl_add_u64 v[154:155], s[10:11], 0, v[148:149]
	s_mov_b32 m0, s55
	ds_read_b128 v[206:209], v171 offset:16384
	ds_read_b128 v[226:229], v171 offset:17408
	ds_read_b128 v[230:233], v171 offset:18432
	ds_read_b128 v[234:237], v171 offset:19456
	ds_read_b128 v[238:241], v171 offset:20480
	ds_read_b128 v[242:245], v171 offset:21504
	ds_read_b128 v[246:249], v171 offset:22528
	ds_read_b128 v[250:253], v171 offset:23552
	global_load_lds_dwordx4 v[154:155], off
	s_add_i32 m0, s55, 0x2000
	s_add_u32 s56, s10, 0x100000
	v_lshl_add_u64 v[176:177], s[10:11], 0, v[146:147]
	s_addc_u32 s57, s11, 0
	s_add_i32 s55, s58, s43
	global_load_lds_dwordx4 v[176:177], off
	v_lshl_add_u64 v[194:195], s[56:57], 0, v[148:149]
	s_mov_b32 m0, s55
	v_lshl_add_u64 v[210:211], s[36:37], 0, v[146:147]
	global_load_lds_dwordx4 v[194:195], off
	v_lshl_add_u64 v[194:195], s[56:57], 0, v[146:147]
	s_add_i32 m0, s55, 0x2000
	s_nop 0
	global_load_lds_dwordx4 v[194:195], off
	v_lshl_add_u64 v[194:195], s[36:37], 0, v[148:149]
	s_mov_b32 m0, s45
	s_nop 0
	global_load_lds_dwordx4 v[194:195], off
	s_mov_b32 m0, s46
	s_nop 0
	global_load_lds_dwordx4 v[210:211], off
	s_setprio 1
	s_waitcnt vmcnt(8) lgkmcnt(0)
	s_barrier
; #define PG8_STAGE(bufoff, gbase, voff) do { _Pragma("unroll") for (int _i = 0; _i < 2; ++_i) \
;         __builtin_amdgcn_global_load_lds((const unsigned*)((const char*)(gbase) + (voff)[_i]), (PG8_LAS unsigned*)(lds + (bufoff) + ldsw + _i * 8192), 16, 0, 0); } while (0)
; #define PG8_LDA(dst, b, h) do { _Pragma("unroll") for (int m = 0; m < 4; ++m) _Pragma("unroll") for (int k = 0; k < 2; ++k) dst[m][k] = *(const PG8_LAS bf16x8*)(lds + PG8_SA(b, h) + aoff + m * 2048 + k * 1024); } while (0)
; #define PG8_LDB(dst, b, h) do { _Pragma("unroll") for (int n = 0; n < 2; ++n) _Pragma("unroll") for (int k = 0; k < 2; ++k) dst[n][k] = *(const PG8_LAS bf16x8*)(lds + PG8_SB(b, h) + boff + n * 2048 + k * 1024); } while (0)
; #define PG8_MMA(ai, bj, At, Bt) do { __builtin_amdgcn_s_setprio(1); _Pragma("unroll") for (int m = 0; m < 4; ++m) _Pragma("unroll") for (int n = 0; n < 2; ++n) _Pragma("unroll") for (int k = 0; k < 2; ++k) \
;         acc[ai][bj][m][n] = __builtin_amdgcn_mfma_f32_16x16x32_bf16(Bt[n][k], At[m][k], acc[ai][bj][m][n], 0, 0, 0); __builtin_amdgcn_s_setprio(0); } while (0)
; #define PG8_WAIT_V(n) asm volatile("s_waitcnt vmcnt(" #n ")" ::: "memory")
; #define PG8_WAIT_L(n) asm volatile("s_waitcnt lgkmcnt(" #n ")" ::: "memory")
; #define PG8_BAR __builtin_amdgcn_s_barrier()
; #define PG8_SCHED __builtin_amdgcn_sched_barrier(0)
; template <class Epi, class Sched, bool ALIGN_EPI, int LMASK = -1, int LMASKB = LMASK>
; __device__ __forceinline__ void gemm_phase(PG8_LAS unsigned char* lds, const Gemm g, const Sched& S, const Epi& E) {
;     ...
;             PG8_WAIT_V(8); PG8_WAIT_L(0); PG8_BAR; PG8_MMA(1, 0, At, B0); PG8_MMA(1, 1, At, B1); PG8_BAR; PG8_SCHED;
;             PG8_LDB(B0, 1, 0); PG8_LDB(B1, 1, 1); PG8_SCHED; PG8_LDA(At, 1, 0); PG8_STAGE(PG8_SA(0, 1), a2 + hstepA, voffA);
;             PG8_WAIT_V(8); PG8_WAIT_L(0); PG8_BAR; PG8_MMA(0, 0, At, B0); PG8_MMA(0, 1, At, B1); PG8_BAR; PG8_SCHED;
;             PG8_LDA(At, 1, 1); PG8_STAGE(PG8_SB(1, 0), b3, voffB); PG8_STAGE(PG8_SB(1, 1), b3 + hstepB, voffB); PG8_STAGE(PG8_SA(1, 0), a3, voffA);
	v_mfma_f32_16x16x32_bf16 v[62:65], v[130:133], v[206:209], v[62:65]
	v_mfma_f32_16x16x32_bf16 v[58:61], v[138:141], v[206:209], v[58:61]
	v_mfma_f32_16x16x32_bf16 v[54:57], v[130:133], v[230:233], v[54:57]
	v_mfma_f32_16x16x32_bf16 v[46:49], v[138:141], v[230:233], v[46:49]
	v_mfma_f32_16x16x32_bf16 v[38:41], v[130:133], v[238:241], v[38:41]
	v_mfma_f32_16x16x32_bf16 v[30:33], v[138:141], v[238:241], v[30:33]
	v_mfma_f32_16x16x32_bf16 v[22:25], v[130:133], v[246:249], v[22:25]
	v_mfma_f32_16x16x32_bf16 v[14:17], v[138:141], v[246:249], v[14:17]
	v_mfma_f32_16x16x32_bf16 v[62:65], v[134:137], v[226:229], v[62:65]
	v_mfma_f32_16x16x32_bf16 v[58:61], v[142:145], v[226:229], v[58:61]
	v_mfma_f32_16x16x32_bf16 v[54:57], v[134:137], v[234:237], v[54:57]
	v_mfma_f32_16x16x32_bf16 v[46:49], v[142:145], v[234:237], v[46:49]
	v_mfma_f32_16x16x32_bf16 v[38:41], v[134:137], v[242:245], v[38:41]
	v_mfma_f32_16x16x32_bf16 v[30:33], v[142:145], v[242:245], v[30:33]
	v_mfma_f32_16x16x32_bf16 v[22:25], v[134:137], v[250:253], v[22:25]
	v_mfma_f32_16x16x32_bf16 v[14:17], v[142:145], v[250:253], v[14:17]
	v_mfma_f32_16x16x32_bf16 v[50:53], v[172:175], v[206:209], v[50:53]
	v_mfma_f32_16x16x32_bf16 v[42:45], v[218:221], v[206:209], v[42:45]
	v_mfma_f32_16x16x32_bf16 v[34:37], v[172:175], v[230:233], v[34:37]
	v_mfma_f32_16x16x32_bf16 v[26:29], v[218:221], v[230:233], v[26:29]
	v_mfma_f32_16x16x32_bf16 v[18:21], v[172:175], v[238:241], v[18:21]
	v_mfma_f32_16x16x32_bf16 v[10:13], v[218:221], v[238:241], v[10:13]
	v_mfma_f32_16x16x32_bf16 v[6:9], v[172:175], v[246:249], v[6:9]
	v_mfma_f32_16x16x32_bf16 v[2:5], v[218:221], v[246:249], v[2:5]
	v_mfma_f32_16x16x32_bf16 v[50:53], v[188:191], v[226:229], v[50:53]
	v_mfma_f32_16x16x32_bf16 v[42:45], v[222:225], v[226:229], v[42:45]
	v_mfma_f32_16x16x32_bf16 v[34:37], v[188:191], v[234:237], v[34:37]
	v_mfma_f32_16x16x32_bf16 v[26:29], v[222:225], v[234:237], v[26:29]
	v_mfma_f32_16x16x32_bf16 v[18:21], v[188:191], v[242:245], v[18:21]
	v_mfma_f32_16x16x32_bf16 v[10:13], v[222:225], v[242:245], v[10:13]
	v_mfma_f32_16x16x32_bf16 v[6:9], v[188:191], v[250:253], v[6:9]
	v_mfma_f32_16x16x32_bf16 v[2:5], v[222:225], v[250:253], v[2:5]
	s_barrier
	s_setprio 0
	s_add_i32 s55, 0, 0x18000
	s_add_i32 s56, 0, 0x1c000
	v_add_u32_e32 v142, s55, v161
	v_add_u32_e32 v156, s56, v161
	ds_read_b128 v[130:133], v142
	ds_read_b128 v[134:137], v142 offset:1024
	ds_read_b128 v[138:141], v142 offset:2048
	ds_read_b128 v[142:145], v142 offset:3072
	ds_read_b128 v[172:175], v156
	ds_read_b128 v[188:191], v156 offset:1024
	ds_read_b128 v[206:209], v156 offset:2048
	ds_read_b128 v[218:221], v156 offset:3072
	s_add_u32 s36, s36, 0x100000
	s_addc_u32 s37, s37, 0
	s_mov_b32 m0, s47
	v_lshl_add_u64 v[212:213], s[36:37], 0, v[148:149]
	ds_read_b128 v[222:225], v171 offset:32768
	ds_read_b128 v[226:229], v171 offset:33792
	ds_read_b128 v[230:233], v171 offset:34816
	ds_read_b128 v[234:237], v171 offset:35840
	ds_read_b128 v[238:241], v171 offset:36864
	ds_read_b128 v[242:245], v171 offset:37888
	ds_read_b128 v[246:249], v171 offset:38912
	ds_read_b128 v[250:253], v171 offset:39936
	global_load_lds_dwordx4 v[212:213], off
	v_lshl_add_u64 v[212:213], s[36:37], 0, v[146:147]
	s_mov_b32 m0, s48
	s_nop 0
	global_load_lds_dwordx4 v[212:213], off
	s_setprio 1
	s_waitcnt vmcnt(8) lgkmcnt(0)
	s_barrier
	v_mfma_f32_16x16x32_bf16 v[126:129], v[130:133], v[222:225], v[126:129]
	v_mfma_f32_16x16x32_bf16 v[122:125], v[138:141], v[222:225], v[122:125]
	v_mfma_f32_16x16x32_bf16 v[118:121], v[130:133], v[230:233], v[118:121]
	v_mfma_f32_16x16x32_bf16 v[110:113], v[138:141], v[230:233], v[110:113]
	v_mfma_f32_16x16x32_bf16 v[102:105], v[130:133], v[238:241], v[102:105]
	v_mfma_f32_16x16x32_bf16 v[94:97], v[138:141], v[238:241], v[94:97]
	v_mfma_f32_16x16x32_bf16 v[86:89], v[130:133], v[246:249], v[86:89]
	v_mfma_f32_16x16x32_bf16 v[78:81], v[138:141], v[246:249], v[78:81]
	v_mfma_f32_16x16x32_bf16 v[126:129], v[134:137], v[226:229], v[126:129]
	v_mfma_f32_16x16x32_bf16 v[122:125], v[142:145], v[226:229], v[122:125]
	v_mfma_f32_16x16x32_bf16 v[118:121], v[134:137], v[234:237], v[118:121]
	v_mfma_f32_16x16x32_bf16 v[110:113], v[142:145], v[234:237], v[110:113]
	v_mfma_f32_16x16x32_bf16 v[102:105], v[134:137], v[242:245], v[102:105]
	v_mfma_f32_16x16x32_bf16 v[94:97], v[142:145], v[242:245], v[94:97]
	v_mfma_f32_16x16x32_bf16 v[86:89], v[134:137], v[250:253], v[86:89]
	v_mfma_f32_16x16x32_bf16 v[78:81], v[142:145], v[250:253], v[78:81]
	v_mfma_f32_16x16x32_bf16 v[114:117], v[172:175], v[222:225], v[114:117]
	v_mfma_f32_16x16x32_bf16 v[106:109], v[206:209], v[222:225], v[106:109]
	v_mfma_f32_16x16x32_bf16 v[98:101], v[172:175], v[230:233], v[98:101]
	v_mfma_f32_16x16x32_bf16 v[90:93], v[206:209], v[230:233], v[90:93]
	v_mfma_f32_16x16x32_bf16 v[82:85], v[172:175], v[238:241], v[82:85]
	v_mfma_f32_16x16x32_bf16 v[74:77], v[206:209], v[238:241], v[74:77]
	v_mfma_f32_16x16x32_bf16 v[70:73], v[172:175], v[246:249], v[70:73]
	v_mfma_f32_16x16x32_bf16 v[66:69], v[206:209], v[246:249], v[66:69]
	v_mfma_f32_16x16x32_bf16 v[114:117], v[188:191], v[226:229], v[114:117]
	v_mfma_f32_16x16x32_bf16 v[106:109], v[218:221], v[226:229], v[106:109]
	v_mfma_f32_16x16x32_bf16 v[98:101], v[188:191], v[234:237], v[98:101]
	v_mfma_f32_16x16x32_bf16 v[90:93], v[218:221], v[234:237], v[90:93]
	v_mfma_f32_16x16x32_bf16 v[82:85], v[188:191], v[242:245], v[82:85]
	v_mfma_f32_16x16x32_bf16 v[74:77], v[218:221], v[242:245], v[74:77]
	v_mfma_f32_16x16x32_bf16 v[70:73], v[188:191], v[250:253], v[70:73]
	v_mfma_f32_16x16x32_bf16 v[66:69], v[218:221], v[250:253], v[66:69]
	s_barrier
; #define PG8_STAGE(bufoff, gbase, voff) do { _Pragma("unroll") for (int _i = 0; _i < 2; ++_i) \
;         __builtin_amdgcn_global_load_lds((const unsigned*)((const char*)(gbase) + (voff)[_i]), (PG8_LAS unsigned*)(lds + (bufoff) + ldsw + _i * 8192), 16, 0, 0); } while (0)
; #define PG8_LDA(dst, b, h) do { _Pragma("unroll") for (int m = 0; m < 4; ++m) _Pragma("unroll") for (int k = 0; k < 2; ++k) dst[m][k] = *(const PG8_LAS bf16x8*)(lds + PG8_SA(b, h) + aoff + m * 2048 + k * 1024); } while (0)
; #define PG8_MMA(ai, bj, At, Bt) do { __builtin_amdgcn_s_setprio(1); _Pragma("unroll") for (int m = 0; m < 4; ++m) _Pragma("unroll") for (int n = 0; n < 2; ++n) _Pragma("unroll") for (int k = 0; k < 2; ++k) \
;         acc[ai][bj][m][n] = __builtin_amdgcn_mfma_f32_16x16x32_bf16(Bt[n][k], At[m][k], acc[ai][bj][m][n], 0, 0, 0); __builtin_amdgcn_s_setprio(0); } while (0)
; #define PG8_WAIT_V(n) asm volatile("s_waitcnt vmcnt(" #n ")" ::: "memory")
; #define PG8_WAIT_L(n) asm volatile("s_waitcnt lgkmcnt(" #n ")" ::: "memory")
; #define PG8_BAR __builtin_amdgcn_s_barrier()
; #define PG8_SCHED __builtin_amdgcn_sched_barrier(0)
; template <class Epi, class Sched, bool ALIGN_EPI, int LMASK = -1, int LMASKB = LMASK>
; __device__ __forceinline__ void gemm_phase(PG8_LAS unsigned char* lds, const Gemm g, const Sched& S, const Epi& E) {
;     ...
;             PG8_LDA(At, 1, 1); PG8_STAGE(PG8_SB(1, 0), b3, voffB); PG8_STAGE(PG8_SB(1, 1), b3 + hstepB, voffB); PG8_STAGE(PG8_SA(1, 0), a3, voffA);
;             PG8_WAIT_V(8); PG8_WAIT_L(0); PG8_BAR; PG8_MMA(1, 0, At, B0); PG8_MMA(1, 1, At, B1); PG8_BAR; PG8_SCHED;
;         }
;         if constexpr (ALIGN_EPI) { if (wr == 0) PG8_BAR; }
	s_setprio 0
	s_add_i32 s36, s55, s43
	v_lshl_add_u64 v[154:155], v[154:155], 0, s[80:81]
	s_mov_b32 m0, s36
	ds_read_b128 v[222:225], v171 offset:49152
	ds_read_b128 v[226:229], v171 offset:50176
	ds_read_b128 v[230:233], v171 offset:51200
	ds_read_b128 v[234:237], v171 offset:52224
	ds_read_b128 v[238:241], v171 offset:53248
	ds_read_b128 v[242:245], v171 offset:54272
	ds_read_b128 v[246:249], v171 offset:55296
	ds_read_b128 v[250:253], v171 offset:56320
	global_load_lds_dwordx4 v[154:155], off
	s_add_i32 m0, s36, 0x2000
	s_add_u32 s10, s10, 0x100800
	v_lshl_add_u64 v[154:155], v[176:177], 0, s[80:81]
	s_addc_u32 s11, s11, 0
	s_add_i32 s36, s56, s43
	global_load_lds_dwordx4 v[154:155], off
	v_lshl_add_u64 v[154:155], s[10:11], 0, v[148:149]
	s_mov_b32 m0, s36
	s_nop 0
	global_load_lds_dwordx4 v[154:155], off
	v_lshl_add_u64 v[154:155], s[10:11], 0, v[146:147]
	s_add_i32 m0, s36, 0x2000
	s_nop 0
	global_load_lds_dwordx4 v[154:155], off
	v_lshl_add_u64 v[154:155], v[194:195], 0, s[80:81]
	s_mov_b32 m0, s49
	s_nop 0
	global_load_lds_dwordx4 v[154:155], off
	v_lshl_add_u64 v[154:155], v[210:211], 0, s[80:81]
	s_mov_b32 m0, s50
	s_nop 0
	global_load_lds_dwordx4 v[154:155], off
	s_setprio 1
	s_waitcnt vmcnt(8) lgkmcnt(0)
	s_barrier
	v_mfma_f32_16x16x32_bf16 v[62:65], v[130:133], v[222:225], v[62:65]
	v_mfma_f32_16x16x32_bf16 v[58:61], v[138:141], v[222:225], v[58:61]
	v_mfma_f32_16x16x32_bf16 v[54:57], v[130:133], v[230:233], v[54:57]
	v_mfma_f32_16x16x32_bf16 v[46:49], v[138:141], v[230:233], v[46:49]
	v_mfma_f32_16x16x32_bf16 v[38:41], v[130:133], v[238:241], v[38:41]
	v_mfma_f32_16x16x32_bf16 v[30:33], v[138:141], v[238:241], v[30:33]
	v_mfma_f32_16x16x32_bf16 v[22:25], v[130:133], v[246:249], v[22:25]
	v_mfma_f32_16x16x32_bf16 v[14:17], v[138:141], v[246:249], v[14:17]
	v_mfma_f32_16x16x32_bf16 v[62:65], v[134:137], v[226:229], v[62:65]
	v_mfma_f32_16x16x32_bf16 v[58:61], v[142:145], v[226:229], v[58:61]
	v_mfma_f32_16x16x32_bf16 v[54:57], v[134:137], v[234:237], v[54:57]
	v_mfma_f32_16x16x32_bf16 v[46:49], v[142:145], v[234:237], v[46:49]
	v_mfma_f32_16x16x32_bf16 v[38:41], v[134:137], v[242:245], v[38:41]
	v_mfma_f32_16x16x32_bf16 v[30:33], v[142:145], v[242:245], v[30:33]
	v_mfma_f32_16x16x32_bf16 v[22:25], v[134:137], v[250:253], v[22:25]
	v_mfma_f32_16x16x32_bf16 v[14:17], v[142:145], v[250:253], v[14:17]
	v_mfma_f32_16x16x32_bf16 v[50:53], v[172:175], v[222:225], v[50:53]
	v_mfma_f32_16x16x32_bf16 v[42:45], v[206:209], v[222:225], v[42:45]
	v_mfma_f32_16x16x32_bf16 v[34:37], v[172:175], v[230:233], v[34:37]
	v_mfma_f32_16x16x32_bf16 v[26:29], v[206:209], v[230:233], v[26:29]
	v_mfma_f32_16x16x32_bf16 v[18:21], v[172:175], v[238:241], v[18:21]
	v_mfma_f32_16x16x32_bf16 v[10:13], v[206:209], v[238:241], v[10:13]
	v_mfma_f32_16x16x32_bf16 v[6:9], v[172:175], v[246:249], v[6:9]
	v_mfma_f32_16x16x32_bf16 v[2:5], v[206:209], v[246:249], v[2:5]
	v_mfma_f32_16x16x32_bf16 v[50:53], v[188:191], v[226:229], v[50:53]
	v_mfma_f32_16x16x32_bf16 v[42:45], v[218:221], v[226:229], v[42:45]
	v_mfma_f32_16x16x32_bf16 v[34:37], v[188:191], v[234:237], v[34:37]
	v_mfma_f32_16x16x32_bf16 v[26:29], v[218:221], v[234:237], v[26:29]
	v_mfma_f32_16x16x32_bf16 v[18:21], v[188:191], v[242:245], v[18:21]
	v_mfma_f32_16x16x32_bf16 v[10:13], v[218:221], v[242:245], v[10:13]
	v_mfma_f32_16x16x32_bf16 v[6:9], v[188:191], v[250:253], v[6:9]
	v_mfma_f32_16x16x32_bf16 v[2:5], v[218:221], v[250:253], v[2:5]
	s_barrier
	s_setprio 0
	s_add_i32 s54, s54, 2
	s_add_u32 s8, s8, 0x1000
	s_addc_u32 s9, s9, 0
	s_add_u32 s27, s27, 0x1000
	s_addc_u32 s29, s29, 0
	s_cmp_gt_u32 s54, 61
	s_cbranch_scc0 .LBB0_284
	s_and_b64 vcc, exec, s[22:23]
	s_cbranch_vccz .LBB0_287
	s_barrier

; #define PG8_STAGE(bufoff, gbase, voff) do { _Pragma("unroll") for (int _i = 0; _i < 2; ++_i) \
;         __builtin_amdgcn_global_load_lds((const unsigned*)((const char*)(gbase) + (voff)[_i]), (PG8_LAS unsigned*)(lds + (bufoff) + ldsw + _i * 8192), 16, 0, 0); } while (0)
; #define PG8_LDA(dst, b, h) do { _Pragma("unroll") for (int m = 0; m < 4; ++m) _Pragma("unroll") for (int k = 0; k < 2; ++k) dst[m][k] = *(const PG8_LAS bf16x8*)(lds + PG8_SA(b, h) + aoff + m * 2048 + k * 1024); } while (0)
; #define PG8_LDB(dst, b, h) do { _Pragma("unroll") for (int n = 0; n < 2; ++n) _Pragma("unroll") for (int k = 0; k < 2; ++k) dst[n][k] = *(const PG8_LAS bf16x8*)(lds + PG8_SB(b, h) + boff + n * 2048 + k * 1024); } while (0)
; #define PG8_MMA(ai, bj, At, Bt) do { __builtin_amdgcn_s_setprio(1); _Pragma("unroll") for (int m = 0; m < 4; ++m) _Pragma("unroll") for (int n = 0; n < 2; ++n) _Pragma("unroll") for (int k = 0; k < 2; ++k) \
;         acc[ai][bj][m][n] = __builtin_amdgcn_mfma_f32_16x16x32_bf16(Bt[n][k], At[m][k], acc[ai][bj][m][n], 0, 0, 0); __builtin_amdgcn_s_setprio(0); } while (0)
; #define PG8_WAIT_V(n) asm volatile("s_waitcnt vmcnt(" #n ")" ::: "memory")
; #define PG8_WAIT_L(n) asm volatile("s_waitcnt lgkmcnt(" #n ")" ::: "memory")
; #define PG8_BAR __builtin_amdgcn_s_barrier()
; #define PG8_SCHED __builtin_amdgcn_sched_barrier(0)
; template <class Epi, class Sched, bool ALIGN_EPI, int LMASK = -1, int LMASKB = LMASK>
; __device__ __forceinline__ void gemm_phase(PG8_LAS unsigned char* lds, const Gemm g, const Sched& S, const Epi& E) {
;     ...
;             PG8_LDB(B0, 0, 0); PG8_LDB(B1, 0, 1); PG8_SCHED; PG8_LDA(At, 0, 0); PG8_STAGE(PG8_SA(1, 1), a1 + hstepA, voffA);
;             PG8_WAIT_V(8); PG8_WAIT_L(0); PG8_BAR; PG8_MMA(0, 0, At, B0); PG8_MMA(0, 1, At, B1); PG8_BAR; PG8_SCHED;
;             PG8_LDA(At, 0, 1); PG8_STAGE(PG8_SB(0, 0), b2, voffB); PG8_STAGE(PG8_SB(0, 1), b2 + hstepB, voffB); PG8_STAGE(PG8_SA(0, 0), a2, voffA);
;             PG8_WAIT_V(8); PG8_WAIT_L(0); PG8_BAR; PG8_MMA(1, 0, At, B0); PG8_MMA(1, 1, At, B1); PG8_BAR; PG8_SCHED;
.LBB0_580:
	s_add_u32 s30, s28, 0xfff00800
	s_addc_u32 s31, s29, -1
	s_add_i32 s51, 0, 0x10000
	s_cmp_eq_u32 s50, 60
	s_cselect_b32 s35, s19, s31
	s_cselect_b32 s34, s25, s30
	v_add_u32_e32 v146, s51, v149
	s_cselect_b32 s31, s17, s49
	s_cselect_b32 s30, s47, s48
	s_add_i32 s54, 0, 0x14000
	ds_read_b128 v[130:133], v146
	ds_read_b128 v[142:145], v146 offset:1024
	ds_read_b128 v[152:155], v146 offset:2048
	ds_read_b128 v[156:159], v146 offset:3072
	v_add_u32_e32 v146, s54, v149
	ds_read_b128 v[160:163], v146
	ds_read_b128 v[164:167], v146 offset:1024
	ds_read_b128 v[168:171], v146 offset:2048
	ds_read_b128 v[172:175], v146 offset:3072
	v_lshl_add_u64 v[146:147], s[28:29], 0, v[138:139]
	s_add_i32 m0, s27, 0xc000
	ds_read_b128 v[188:191], v151
	ds_read_b128 v[206:209], v151 offset:1024
	ds_read_b128 v[218:221], v151 offset:2048
	ds_read_b128 v[222:225], v151 offset:3072
	ds_read_b128 v[226:229], v151 offset:4096
	ds_read_b128 v[230:233], v151 offset:5120
	ds_read_b128 v[234:237], v151 offset:6144
	ds_read_b128 v[238:241], v151 offset:7168
	global_load_lds_dwordx4 v[146:147], off
	v_lshl_add_u64 v[146:147], s[28:29], 0, v[140:141]
	s_add_i32 m0, s27, 0xe000
	s_nop 0
	global_load_lds_dwordx4 v[146:147], off
	s_setprio 1
	s_waitcnt vmcnt(8) lgkmcnt(0)
	s_barrier
	v_mfma_f32_16x16x32_bf16 v[126:129], v[130:133], v[188:191], v[126:129]
	v_mfma_f32_16x16x32_bf16 v[122:125], v[152:155], v[188:191], v[122:125]
	v_mfma_f32_16x16x32_bf16 v[110:113], v[130:133], v[218:221], v[110:113]
	v_mfma_f32_16x16x32_bf16 v[106:109], v[152:155], v[218:221], v[106:109]
	v_mfma_f32_16x16x32_bf16 v[94:97], v[130:133], v[226:229], v[94:97]
	v_mfma_f32_16x16x32_bf16 v[90:93], v[152:155], v[226:229], v[90:93]
	v_mfma_f32_16x16x32_bf16 v[78:81], v[130:133], v[234:237], v[78:81]
	v_mfma_f32_16x16x32_bf16 v[74:77], v[152:155], v[234:237], v[74:77]
	v_mfma_f32_16x16x32_bf16 v[126:129], v[142:145], v[206:209], v[126:129]
	v_mfma_f32_16x16x32_bf16 v[122:125], v[156:159], v[206:209], v[122:125]
	v_mfma_f32_16x16x32_bf16 v[110:113], v[142:145], v[222:225], v[110:113]
	v_mfma_f32_16x16x32_bf16 v[106:109], v[156:159], v[222:225], v[106:109]
	v_mfma_f32_16x16x32_bf16 v[94:97], v[142:145], v[230:233], v[94:97]
	v_mfma_f32_16x16x32_bf16 v[90:93], v[156:159], v[230:233], v[90:93]
	v_mfma_f32_16x16x32_bf16 v[78:81], v[142:145], v[238:241], v[78:81]
	v_mfma_f32_16x16x32_bf16 v[74:77], v[156:159], v[238:241], v[74:77]
	v_mfma_f32_16x16x32_bf16 v[118:121], v[160:163], v[188:191], v[118:121]
	v_mfma_f32_16x16x32_bf16 v[114:117], v[168:171], v[188:191], v[114:117]
	v_mfma_f32_16x16x32_bf16 v[102:105], v[160:163], v[218:221], v[102:105]
	v_mfma_f32_16x16x32_bf16 v[98:101], v[168:171], v[218:221], v[98:101]
	v_mfma_f32_16x16x32_bf16 v[86:89], v[160:163], v[226:229], v[86:89]
	v_mfma_f32_16x16x32_bf16 v[82:85], v[168:171], v[226:229], v[82:85]
	v_mfma_f32_16x16x32_bf16 v[70:73], v[160:163], v[234:237], v[70:73]
	v_mfma_f32_16x16x32_bf16 v[66:69], v[168:171], v[234:237], v[66:69]
	v_mfma_f32_16x16x32_bf16 v[118:121], v[164:167], v[206:209], v[118:121]
	v_mfma_f32_16x16x32_bf16 v[114:117], v[172:175], v[206:209], v[114:117]
	v_mfma_f32_16x16x32_bf16 v[102:105], v[164:167], v[222:225], v[102:105]
	v_mfma_f32_16x16x32_bf16 v[98:101], v[172:175], v[222:225], v[98:101]
	v_mfma_f32_16x16x32_bf16 v[86:89], v[164:167], v[230:233], v[86:89]
	v_mfma_f32_16x16x32_bf16 v[82:85], v[172:175], v[230:233], v[82:85]
	v_mfma_f32_16x16x32_bf16 v[70:73], v[164:167], v[238:241], v[70:73]
	v_mfma_f32_16x16x32_bf16 v[66:69], v[172:175], v[238:241], v[66:69]
	s_barrier
	s_setprio 0
	s_add_i32 s51, s51, s38
	v_lshl_add_u64 v[146:147], s[30:31], 0, v[134:135]
	s_mov_b32 m0, s51
	ds_read_b128 v[188:191], v151 offset:16384
	ds_read_b128 v[206:209], v151 offset:17408
	ds_read_b128 v[218:221], v151 offset:18432
	ds_read_b128 v[222:225], v151 offset:19456
	ds_read_b128 v[226:229], v151 offset:20480
	ds_read_b128 v[230:233], v151 offset:21504
	ds_read_b128 v[234:237], v151 offset:22528
	ds_read_b128 v[238:241], v151 offset:23552
	global_load_lds_dwordx4 v[146:147], off
	s_add_i32 m0, s51, 0x2000
	s_add_u32 s52, s30, 0x100000
	v_lshl_add_u64 v[176:177], s[30:31], 0, v[136:137]
	s_addc_u32 s53, s31, 0
	s_add_i32 s51, s54, s38
	global_load_lds_dwordx4 v[176:177], off
	v_lshl_add_u64 v[194:195], s[52:53], 0, v[134:135]
	s_mov_b32 m0, s51
	v_lshl_add_u64 v[210:211], s[34:35], 0, v[136:137]
	global_load_lds_dwordx4 v[194:195], off
	v_lshl_add_u64 v[194:195], s[52:53], 0, v[136:137]
	s_add_i32 m0, s51, 0x2000
	s_nop 0
	global_load_lds_dwordx4 v[194:195], off
	v_lshl_add_u64 v[194:195], s[34:35], 0, v[134:135]
	s_mov_b32 m0, s27
	s_nop 0
	global_load_lds_dwordx4 v[194:195], off
	s_mov_b32 m0, s39
	s_nop 0
	global_load_lds_dwordx4 v[210:211], off
	s_setprio 1
	s_waitcnt vmcnt(8) lgkmcnt(0)
	s_barrier
; #define PG8_STAGE(bufoff, gbase, voff) do { _Pragma("unroll") for (int _i = 0; _i < 2; ++_i) \
;         __builtin_amdgcn_global_load_lds((const unsigned*)((const char*)(gbase) + (voff)[_i]), (PG8_LAS unsigned*)(lds + (bufoff) + ldsw + _i * 8192), 16, 0, 0); } while (0)
; #define PG8_LDA(dst, b, h) do { _Pragma("unroll") for (int m = 0; m < 4; ++m) _Pragma("unroll") for (int k = 0; k < 2; ++k) dst[m][k] = *(const PG8_LAS bf16x8*)(lds + PG8_SA(b, h) + aoff + m * 2048 + k * 1024); } while (0)
; #define PG8_LDB(dst, b, h) do { _Pragma("unroll") for (int n = 0; n < 2; ++n) _Pragma("unroll") for (int k = 0; k < 2; ++k) dst[n][k] = *(const PG8_LAS bf16x8*)(lds + PG8_SB(b, h) + boff + n * 2048 + k * 1024); } while (0)
; #define PG8_MMA(ai, bj, At, Bt) do { __builtin_amdgcn_s_setprio(1); _Pragma("unroll") for (int m = 0; m < 4; ++m) _Pragma("unroll") for (int n = 0; n < 2; ++n) _Pragma("unroll") for (int k = 0; k < 2; ++k) \
;         acc[ai][bj][m][n] = __builtin_amdgcn_mfma_f32_16x16x32_bf16(Bt[n][k], At[m][k], acc[ai][bj][m][n], 0, 0, 0); __builtin_amdgcn_s_setprio(0); } while (0)
; #define PG8_WAIT_V(n) asm volatile("s_waitcnt vmcnt(" #n ")" ::: "memory")
; #define PG8_WAIT_L(n) asm volatile("s_waitcnt lgkmcnt(" #n ")" ::: "memory")
; #define PG8_BAR __builtin_amdgcn_s_barrier()
; #define PG8_SCHED __builtin_amdgcn_sched_barrier(0)
; template <class Epi, class Sched, bool ALIGN_EPI, int LMASK = -1, int LMASKB = LMASK>
; __device__ __forceinline__ void gemm_phase(PG8_LAS unsigned char* lds, const Gemm g, const Sched& S, const Epi& E) {
;     ...
;             PG8_WAIT_V(8); PG8_WAIT_L(0); PG8_BAR; PG8_MMA(1, 0, At, B0); PG8_MMA(1, 1, At, B1); PG8_BAR; PG8_SCHED;
;             PG8_LDB(B0, 1, 0); PG8_LDB(B1, 1, 1); PG8_SCHED; PG8_LDA(At, 1, 0); PG8_STAGE(PG8_SA(0, 1), a2 + hstepA, voffA);
;             PG8_WAIT_V(8); PG8_WAIT_L(0); PG8_BAR; PG8_MMA(0, 0, At, B0); PG8_MMA(0, 1, At, B1); PG8_BAR; PG8_SCHED;
;             PG8_LDA(At, 1, 1); PG8_STAGE(PG8_SB(1, 0), b3, voffB); PG8_STAGE(PG8_SB(1, 1), b3 + hstepB, voffB); PG8_STAGE(PG8_SA(1, 0), a3, voffA);
	v_mfma_f32_16x16x32_bf16 v[62:65], v[130:133], v[188:191], v[62:65]
	v_mfma_f32_16x16x32_bf16 v[58:61], v[152:155], v[188:191], v[58:61]
	v_mfma_f32_16x16x32_bf16 v[46:49], v[130:133], v[218:221], v[46:49]
	v_mfma_f32_16x16x32_bf16 v[42:45], v[152:155], v[218:221], v[42:45]
	v_mfma_f32_16x16x32_bf16 v[30:33], v[130:133], v[226:229], v[30:33]
	v_mfma_f32_16x16x32_bf16 v[26:29], v[152:155], v[226:229], v[26:29]
	v_mfma_f32_16x16x32_bf16 v[14:17], v[130:133], v[234:237], v[14:17]
	v_mfma_f32_16x16x32_bf16 v[10:13], v[152:155], v[234:237], v[10:13]
	v_mfma_f32_16x16x32_bf16 v[62:65], v[142:145], v[206:209], v[62:65]
	v_mfma_f32_16x16x32_bf16 v[58:61], v[156:159], v[206:209], v[58:61]
	v_mfma_f32_16x16x32_bf16 v[46:49], v[142:145], v[222:225], v[46:49]
	v_mfma_f32_16x16x32_bf16 v[42:45], v[156:159], v[222:225], v[42:45]
	v_mfma_f32_16x16x32_bf16 v[30:33], v[142:145], v[230:233], v[30:33]
	v_mfma_f32_16x16x32_bf16 v[26:29], v[156:159], v[230:233], v[26:29]
	v_mfma_f32_16x16x32_bf16 v[14:17], v[142:145], v[238:241], v[14:17]
	v_mfma_f32_16x16x32_bf16 v[10:13], v[156:159], v[238:241], v[10:13]
	v_mfma_f32_16x16x32_bf16 v[54:57], v[160:163], v[188:191], v[54:57]
	v_mfma_f32_16x16x32_bf16 v[50:53], v[168:171], v[188:191], v[50:53]
	v_mfma_f32_16x16x32_bf16 v[38:41], v[160:163], v[218:221], v[38:41]
	v_mfma_f32_16x16x32_bf16 v[34:37], v[168:171], v[218:221], v[34:37]
	v_mfma_f32_16x16x32_bf16 v[22:25], v[160:163], v[226:229], v[22:25]
	v_mfma_f32_16x16x32_bf16 v[18:21], v[168:171], v[226:229], v[18:21]
	v_mfma_f32_16x16x32_bf16 v[6:9], v[160:163], v[234:237], v[6:9]
	v_mfma_f32_16x16x32_bf16 v[2:5], v[168:171], v[234:237], v[2:5]
	v_mfma_f32_16x16x32_bf16 v[54:57], v[164:167], v[206:209], v[54:57]
	v_mfma_f32_16x16x32_bf16 v[50:53], v[172:175], v[206:209], v[50:53]
	v_mfma_f32_16x16x32_bf16 v[38:41], v[164:167], v[222:225], v[38:41]
	v_mfma_f32_16x16x32_bf16 v[34:37], v[172:175], v[222:225], v[34:37]
	v_mfma_f32_16x16x32_bf16 v[22:25], v[164:167], v[230:233], v[22:25]
	v_mfma_f32_16x16x32_bf16 v[18:21], v[172:175], v[230:233], v[18:21]
	v_mfma_f32_16x16x32_bf16 v[6:9], v[164:167], v[238:241], v[6:9]
	v_mfma_f32_16x16x32_bf16 v[2:5], v[172:175], v[238:241], v[2:5]
	s_barrier
	s_setprio 0
	s_add_i32 s51, 0, 0x18000
	s_add_i32 s52, 0, 0x1c000
	v_add_u32_e32 v156, s51, v149
	v_add_u32_e32 v172, s52, v149
	ds_read_b128 v[130:133], v156
	ds_read_b128 v[142:145], v156 offset:1024
	ds_read_b128 v[152:155], v156 offset:2048
	ds_read_b128 v[156:159], v156 offset:3072
	ds_read_b128 v[160:163], v172
	ds_read_b128 v[164:167], v172 offset:1024
	ds_read_b128 v[168:171], v172 offset:2048
	ds_read_b128 v[172:175], v172 offset:3072
	s_add_u32 s34, s34, 0x100000
	s_addc_u32 s35, s35, 0
	s_mov_b32 m0, s40
	v_lshl_add_u64 v[212:213], s[34:35], 0, v[134:135]
	ds_read_b128 v[188:191], v151 offset:32768
	ds_read_b128 v[206:209], v151 offset:33792
	ds_read_b128 v[218:221], v151 offset:34816
	ds_read_b128 v[222:225], v151 offset:35840
	ds_read_b128 v[226:229], v151 offset:36864
	ds_read_b128 v[230:233], v151 offset:37888
	ds_read_b128 v[234:237], v151 offset:38912
	ds_read_b128 v[238:241], v151 offset:39936
	global_load_lds_dwordx4 v[212:213], off
	v_lshl_add_u64 v[212:213], s[34:35], 0, v[136:137]
	s_mov_b32 m0, s41
	s_nop 0
	global_load_lds_dwordx4 v[212:213], off
	s_setprio 1
	s_waitcnt vmcnt(8) lgkmcnt(0)
	s_barrier
	v_mfma_f32_16x16x32_bf16 v[126:129], v[130:133], v[188:191], v[126:129]
	v_mfma_f32_16x16x32_bf16 v[122:125], v[152:155], v[188:191], v[122:125]
	v_mfma_f32_16x16x32_bf16 v[110:113], v[130:133], v[218:221], v[110:113]
	v_mfma_f32_16x16x32_bf16 v[106:109], v[152:155], v[218:221], v[106:109]
	v_mfma_f32_16x16x32_bf16 v[94:97], v[130:133], v[226:229], v[94:97]
	v_mfma_f32_16x16x32_bf16 v[90:93], v[152:155], v[226:229], v[90:93]
	v_mfma_f32_16x16x32_bf16 v[78:81], v[130:133], v[234:237], v[78:81]
	v_mfma_f32_16x16x32_bf16 v[74:77], v[152:155], v[234:237], v[74:77]
	v_mfma_f32_16x16x32_bf16 v[126:129], v[142:145], v[206:209], v[126:129]
	v_mfma_f32_16x16x32_bf16 v[122:125], v[156:159], v[206:209], v[122:125]
	v_mfma_f32_16x16x32_bf16 v[110:113], v[142:145], v[222:225], v[110:113]
	v_mfma_f32_16x16x32_bf16 v[106:109], v[156:159], v[222:225], v[106:109]
	v_mfma_f32_16x16x32_bf16 v[94:97], v[142:145], v[230:233], v[94:97]
	v_mfma_f32_16x16x32_bf16 v[90:93], v[156:159], v[230:233], v[90:93]
	v_mfma_f32_16x16x32_bf16 v[78:81], v[142:145], v[238:241], v[78:81]
	v_mfma_f32_16x16x32_bf16 v[74:77], v[156:159], v[238:241], v[74:77]
	v_mfma_f32_16x16x32_bf16 v[118:121], v[160:163], v[188:191], v[118:121]
	v_mfma_f32_16x16x32_bf16 v[114:117], v[168:171], v[188:191], v[114:117]
	v_mfma_f32_16x16x32_bf16 v[102:105], v[160:163], v[218:221], v[102:105]
	v_mfma_f32_16x16x32_bf16 v[98:101], v[168:171], v[218:221], v[98:101]
	v_mfma_f32_16x16x32_bf16 v[86:89], v[160:163], v[226:229], v[86:89]
	v_mfma_f32_16x16x32_bf16 v[82:85], v[168:171], v[226:229], v[82:85]
	v_mfma_f32_16x16x32_bf16 v[70:73], v[160:163], v[234:237], v[70:73]
	v_mfma_f32_16x16x32_bf16 v[66:69], v[168:171], v[234:237], v[66:69]
	v_mfma_f32_16x16x32_bf16 v[118:121], v[164:167], v[206:209], v[118:121]
	v_mfma_f32_16x16x32_bf16 v[114:117], v[172:175], v[206:209], v[114:117]
	v_mfma_f32_16x16x32_bf16 v[102:105], v[164:167], v[222:225], v[102:105]
	v_mfma_f32_16x16x32_bf16 v[98:101], v[172:175], v[222:225], v[98:101]
	v_mfma_f32_16x16x32_bf16 v[86:89], v[164:167], v[230:233], v[86:89]
	v_mfma_f32_16x16x32_bf16 v[82:85], v[172:175], v[230:233], v[82:85]
	v_mfma_f32_16x16x32_bf16 v[70:73], v[164:167], v[238:241], v[70:73]
	v_mfma_f32_16x16x32_bf16 v[66:69], v[172:175], v[238:241], v[66:69]
	s_barrier
; #define PG8_STAGE(bufoff, gbase, voff) do { _Pragma("unroll") for (int _i = 0; _i < 2; ++_i) \
;         __builtin_amdgcn_global_load_lds((const unsigned*)((const char*)(gbase) + (voff)[_i]), (PG8_LAS unsigned*)(lds + (bufoff) + ldsw + _i * 8192), 16, 0, 0); } while (0)
; #define PG8_LDA(dst, b, h) do { _Pragma("unroll") for (int m = 0; m < 4; ++m) _Pragma("unroll") for (int k = 0; k < 2; ++k) dst[m][k] = *(const PG8_LAS bf16x8*)(lds + PG8_SA(b, h) + aoff + m * 2048 + k * 1024); } while (0)
; #define PG8_MMA(ai, bj, At, Bt) do { __builtin_amdgcn_s_setprio(1); _Pragma("unroll") for (int m = 0; m < 4; ++m) _Pragma("unroll") for (int n = 0; n < 2; ++n) _Pragma("unroll") for (int k = 0; k < 2; ++k) \
;         acc[ai][bj][m][n] = __builtin_amdgcn_mfma_f32_16x16x32_bf16(Bt[n][k], At[m][k], acc[ai][bj][m][n], 0, 0, 0); __builtin_amdgcn_s_setprio(0); } while (0)
; #define PG8_WAIT_V(n) asm volatile("s_waitcnt vmcnt(" #n ")" ::: "memory")
; #define PG8_WAIT_L(n) asm volatile("s_waitcnt lgkmcnt(" #n ")" ::: "memory")
; #define PG8_BAR __builtin_amdgcn_s_barrier()
; #define PG8_SCHED __builtin_amdgcn_sched_barrier(0)
; template <class Epi, class Sched, bool ALIGN_EPI, int LMASK = -1, int LMASKB = LMASK>
; __device__ __forceinline__ void gemm_phase(PG8_LAS unsigned char* lds, const Gemm g, const Sched& S, const Epi& E) {
;     ...
;             PG8_LDA(At, 1, 1); PG8_STAGE(PG8_SB(1, 0), b3, voffB); PG8_STAGE(PG8_SB(1, 1), b3 + hstepB, voffB); PG8_STAGE(PG8_SA(1, 0), a3, voffA);
;             PG8_WAIT_V(8); PG8_WAIT_L(0); PG8_BAR; PG8_MMA(1, 0, At, B0); PG8_MMA(1, 1, At, B1); PG8_BAR; PG8_SCHED;
;         }
;         if constexpr (ALIGN_EPI) { if (wr == 0) PG8_BAR; }
	s_setprio 0
	s_add_i32 s34, s51, s38
	v_lshl_add_u64 v[146:147], v[146:147], 0, s[80:81]
	s_mov_b32 m0, s34
	ds_read_b128 v[188:191], v151 offset:49152
	ds_read_b128 v[206:209], v151 offset:50176
	ds_read_b128 v[218:221], v151 offset:51200
	ds_read_b128 v[222:225], v151 offset:52224
	ds_read_b128 v[226:229], v151 offset:53248
	ds_read_b128 v[230:233], v151 offset:54272
	ds_read_b128 v[234:237], v151 offset:55296
	ds_read_b128 v[238:241], v151 offset:56320
	global_load_lds_dwordx4 v[146:147], off
	s_add_i32 m0, s34, 0x2000
	s_add_u32 s30, s30, 0x100800
	v_lshl_add_u64 v[146:147], v[176:177], 0, s[80:81]
	s_addc_u32 s31, s31, 0
	s_add_i32 s34, s52, s38
	global_load_lds_dwordx4 v[146:147], off
	v_lshl_add_u64 v[146:147], s[30:31], 0, v[134:135]
	s_mov_b32 m0, s34
	s_nop 0
	global_load_lds_dwordx4 v[146:147], off
	v_lshl_add_u64 v[146:147], s[30:31], 0, v[136:137]
	s_add_i32 m0, s34, 0x2000
	s_nop 0
	global_load_lds_dwordx4 v[146:147], off
	v_lshl_add_u64 v[146:147], v[194:195], 0, s[80:81]
	s_mov_b32 m0, s42
	s_nop 0
	global_load_lds_dwordx4 v[146:147], off
	v_lshl_add_u64 v[146:147], v[210:211], 0, s[80:81]
	s_mov_b32 m0, s43
	s_nop 0
	global_load_lds_dwordx4 v[146:147], off
	s_setprio 1
	s_waitcnt vmcnt(8) lgkmcnt(0)
	s_barrier
	v_mfma_f32_16x16x32_bf16 v[62:65], v[130:133], v[188:191], v[62:65]
	v_mfma_f32_16x16x32_bf16 v[58:61], v[152:155], v[188:191], v[58:61]
	v_mfma_f32_16x16x32_bf16 v[46:49], v[130:133], v[218:221], v[46:49]
	v_mfma_f32_16x16x32_bf16 v[42:45], v[152:155], v[218:221], v[42:45]
	v_mfma_f32_16x16x32_bf16 v[30:33], v[130:133], v[226:229], v[30:33]
	v_mfma_f32_16x16x32_bf16 v[26:29], v[152:155], v[226:229], v[26:29]
	v_mfma_f32_16x16x32_bf16 v[14:17], v[130:133], v[234:237], v[14:17]
	v_mfma_f32_16x16x32_bf16 v[10:13], v[152:155], v[234:237], v[10:13]
	v_mfma_f32_16x16x32_bf16 v[62:65], v[142:145], v[206:209], v[62:65]
	v_mfma_f32_16x16x32_bf16 v[58:61], v[156:159], v[206:209], v[58:61]
	v_mfma_f32_16x16x32_bf16 v[46:49], v[142:145], v[222:225], v[46:49]
	v_mfma_f32_16x16x32_bf16 v[42:45], v[156:159], v[222:225], v[42:45]
	v_mfma_f32_16x16x32_bf16 v[30:33], v[142:145], v[230:233], v[30:33]
	v_mfma_f32_16x16x32_bf16 v[26:29], v[156:159], v[230:233], v[26:29]
	v_mfma_f32_16x16x32_bf16 v[14:17], v[142:145], v[238:241], v[14:17]
	v_mfma_f32_16x16x32_bf16 v[10:13], v[156:159], v[238:241], v[10:13]
	v_mfma_f32_16x16x32_bf16 v[54:57], v[160:163], v[188:191], v[54:57]
	v_mfma_f32_16x16x32_bf16 v[50:53], v[168:171], v[188:191], v[50:53]
	v_mfma_f32_16x16x32_bf16 v[38:41], v[160:163], v[218:221], v[38:41]
	v_mfma_f32_16x16x32_bf16 v[34:37], v[168:171], v[218:221], v[34:37]
	v_mfma_f32_16x16x32_bf16 v[22:25], v[160:163], v[226:229], v[22:25]
	v_mfma_f32_16x16x32_bf16 v[18:21], v[168:171], v[226:229], v[18:21]
	v_mfma_f32_16x16x32_bf16 v[6:9], v[160:163], v[234:237], v[6:9]
	v_mfma_f32_16x16x32_bf16 v[2:5], v[168:171], v[234:237], v[2:5]
	v_mfma_f32_16x16x32_bf16 v[54:57], v[164:167], v[206:209], v[54:57]
	v_mfma_f32_16x16x32_bf16 v[50:53], v[172:175], v[206:209], v[50:53]
	v_mfma_f32_16x16x32_bf16 v[38:41], v[164:167], v[222:225], v[38:41]
	v_mfma_f32_16x16x32_bf16 v[34:37], v[172:175], v[222:225], v[34:37]
	v_mfma_f32_16x16x32_bf16 v[22:25], v[164:167], v[230:233], v[22:25]
	v_mfma_f32_16x16x32_bf16 v[18:21], v[172:175], v[230:233], v[18:21]
	v_mfma_f32_16x16x32_bf16 v[6:9], v[164:167], v[238:241], v[6:9]
	v_mfma_f32_16x16x32_bf16 v[2:5], v[172:175], v[238:241], v[2:5]
	s_barrier
	s_setprio 0
	s_add_i32 s50, s50, 2
	s_add_u32 s28, s28, 0x1000
	s_addc_u32 s29, s29, 0
	s_add_u32 s48, s48, 0x1000
	s_addc_u32 s49, s49, 0
	s_cmp_gt_u32 s50, 61
	s_cbranch_scc0 .LBB0_580
	s_and_b64 vcc, exec, s[14:15]
	s_cbranch_vccz .LBB0_583
	s_barrier

; #define PG8_STAGE(bufoff, gbase, voff) do { _Pragma("unroll") for (int _i = 0; _i < 2; ++_i) \
;         __builtin_amdgcn_global_load_lds((const unsigned*)((const char*)(gbase) + (voff)[_i]), (PG8_LAS unsigned*)(lds + (bufoff) + ldsw + _i * 8192), 16, 0, 0); } while (0)
; #define PG8_LDA(dst, b, h) do { _Pragma("unroll") for (int m = 0; m < 4; ++m) _Pragma("unroll") for (int k = 0; k < 2; ++k) dst[m][k] = *(const PG8_LAS bf16x8*)(lds + PG8_SA(b, h) + aoff + m * 2048 + k * 1024); } while (0)
; #define PG8_LDB(dst, b, h) do { _Pragma("unroll") for (int n = 0; n < 2; ++n) _Pragma("unroll") for (int k = 0; k < 2; ++k) dst[n][k] = *(const PG8_LAS bf16x8*)(lds + PG8_SB(b, h) + boff + n * 2048 + k * 1024); } while (0)
; #define PG8_MMA(ai, bj, At, Bt) do { __builtin_amdgcn_s_setprio(1); _Pragma("unroll") for (int m = 0; m < 4; ++m) _Pragma("unroll") for (int n = 0; n < 2; ++n) _Pragma("unroll") for (int k = 0; k < 2; ++k) \
;         acc[ai][bj][m][n] = __builtin_amdgcn_mfma_f32_16x16x32_bf16(Bt[n][k], At[m][k], acc[ai][bj][m][n], 0, 0, 0); __builtin_amdgcn_s_setprio(0); } while (0)
; #define PG8_WAIT_V(n) asm volatile("s_waitcnt vmcnt(" #n ")" ::: "memory")
; #define PG8_WAIT_L(n) asm volatile("s_waitcnt lgkmcnt(" #n ")" ::: "memory")
; #define PG8_BAR __builtin_amdgcn_s_barrier()
; #define PG8_SCHED __builtin_amdgcn_sched_barrier(0)
; template <class Epi, class Sched, bool ALIGN_EPI, int LMASK = -1, int LMASKB = LMASK>
; __device__ __forceinline__ void gemm_phase(PG8_LAS unsigned char* lds, const Gemm g, const Sched& S, const Epi& E) {
;     ...
;             PG8_LDB(B0, 0, 0); PG8_LDB(B1, 0, 1); PG8_SCHED; PG8_LDA(At, 0, 0); PG8_STAGE(PG8_SA(1, 1), a1 + hstepA, voffA);
;             PG8_WAIT_V(8); PG8_WAIT_L(0); PG8_BAR; PG8_MMA(0, 0, At, B0); PG8_MMA(0, 1, At, B1); PG8_BAR; PG8_SCHED;
;             PG8_LDA(At, 0, 1); PG8_STAGE(PG8_SB(0, 0), b2, voffB); PG8_STAGE(PG8_SB(0, 1), b2 + hstepB, voffB); PG8_STAGE(PG8_SA(0, 0), a2, voffA);
;             PG8_WAIT_V(8); PG8_WAIT_L(0); PG8_BAR; PG8_MMA(1, 0, At, B0); PG8_MMA(1, 1, At, B1); PG8_BAR; PG8_SCHED;
.LBB0_678:
	s_add_u32 s26, s24, 0xfff00800
	s_addc_u32 s27, s25, -1
	s_add_i32 s50, 0, 0x10000
	s_cmp_eq_u32 s49, 60
	s_cselect_b32 s29, s1, s27
	s_cselect_b32 s28, s2, s26
	s_cselect_b32 s27, s15, s48
	s_cselect_b32 s26, s17, s47
	s_add_i32 s52, 0, 0x14000
	v_add_u32_e32 v154, s50, v143
	v_add_u32_e32 v170, s52, v143
	ds_read_b128 v[138:141], v154
	ds_read_b128 v[146:149], v154 offset:1024
	ds_read_b128 v[150:153], v154 offset:2048
	ds_read_b128 v[154:157], v154 offset:3072
	ds_read_b128 v[158:161], v170
	ds_read_b128 v[162:165], v170 offset:1024
	ds_read_b128 v[166:169], v170 offset:2048
	ds_read_b128 v[170:173], v170 offset:3072
	v_lshl_add_u64 v[194:195], s[24:25], 0, v[134:135]
	s_add_i32 m0, s23, 0xc000
	ds_read_b128 v[174:177], v145
	ds_read_b128 v[188:191], v145 offset:1024
	ds_read_b128 v[206:209], v145 offset:2048
	ds_read_b128 v[218:221], v145 offset:3072
	ds_read_b128 v[222:225], v145 offset:4096
	ds_read_b128 v[226:229], v145 offset:5120
	ds_read_b128 v[230:233], v145 offset:6144
	ds_read_b128 v[234:237], v145 offset:7168
	global_load_lds_dwordx4 v[194:195], off
	v_lshl_add_u64 v[194:195], s[24:25], 0, v[136:137]
	s_add_i32 m0, s23, 0xe000
	s_nop 0
	global_load_lds_dwordx4 v[194:195], off
	s_setprio 1
	s_waitcnt vmcnt(8) lgkmcnt(0)
	s_barrier
	v_mfma_f32_16x16x32_bf16 v[126:129], v[138:141], v[174:177], v[126:129]
	v_mfma_f32_16x16x32_bf16 v[122:125], v[150:153], v[174:177], v[122:125]
	v_mfma_f32_16x16x32_bf16 v[110:113], v[138:141], v[206:209], v[110:113]
	v_mfma_f32_16x16x32_bf16 v[106:109], v[150:153], v[206:209], v[106:109]
	v_mfma_f32_16x16x32_bf16 v[94:97], v[138:141], v[222:225], v[94:97]
	v_mfma_f32_16x16x32_bf16 v[90:93], v[150:153], v[222:225], v[90:93]
	v_mfma_f32_16x16x32_bf16 v[78:81], v[138:141], v[230:233], v[78:81]
	v_mfma_f32_16x16x32_bf16 v[74:77], v[150:153], v[230:233], v[74:77]
	v_mfma_f32_16x16x32_bf16 v[126:129], v[146:149], v[188:191], v[126:129]
	v_mfma_f32_16x16x32_bf16 v[122:125], v[154:157], v[188:191], v[122:125]
	v_mfma_f32_16x16x32_bf16 v[110:113], v[146:149], v[218:221], v[110:113]
	v_mfma_f32_16x16x32_bf16 v[106:109], v[154:157], v[218:221], v[106:109]
	v_mfma_f32_16x16x32_bf16 v[94:97], v[146:149], v[226:229], v[94:97]
	v_mfma_f32_16x16x32_bf16 v[90:93], v[154:157], v[226:229], v[90:93]
	v_mfma_f32_16x16x32_bf16 v[78:81], v[146:149], v[234:237], v[78:81]
	v_mfma_f32_16x16x32_bf16 v[74:77], v[154:157], v[234:237], v[74:77]
	v_mfma_f32_16x16x32_bf16 v[118:121], v[158:161], v[174:177], v[118:121]
	v_mfma_f32_16x16x32_bf16 v[114:117], v[166:169], v[174:177], v[114:117]
	v_mfma_f32_16x16x32_bf16 v[102:105], v[158:161], v[206:209], v[102:105]
	v_mfma_f32_16x16x32_bf16 v[98:101], v[166:169], v[206:209], v[98:101]
	v_mfma_f32_16x16x32_bf16 v[86:89], v[158:161], v[222:225], v[86:89]
	v_mfma_f32_16x16x32_bf16 v[82:85], v[166:169], v[222:225], v[82:85]
	v_mfma_f32_16x16x32_bf16 v[70:73], v[158:161], v[230:233], v[70:73]
	v_mfma_f32_16x16x32_bf16 v[66:69], v[166:169], v[230:233], v[66:69]
	v_mfma_f32_16x16x32_bf16 v[118:121], v[162:165], v[188:191], v[118:121]
	v_mfma_f32_16x16x32_bf16 v[114:117], v[170:173], v[188:191], v[114:117]
	v_mfma_f32_16x16x32_bf16 v[102:105], v[162:165], v[218:221], v[102:105]
	v_mfma_f32_16x16x32_bf16 v[98:101], v[170:173], v[218:221], v[98:101]
	v_mfma_f32_16x16x32_bf16 v[86:89], v[162:165], v[226:229], v[86:89]
	v_mfma_f32_16x16x32_bf16 v[82:85], v[170:173], v[226:229], v[82:85]
	v_mfma_f32_16x16x32_bf16 v[70:73], v[162:165], v[234:237], v[70:73]
	v_mfma_f32_16x16x32_bf16 v[66:69], v[170:173], v[234:237], v[66:69]
	s_barrier
	s_setprio 0
	s_add_i32 s50, s50, s38
	v_lshl_add_u64 v[194:195], s[26:27], 0, v[130:131]
	s_mov_b32 m0, s50
	ds_read_b128 v[174:177], v145 offset:16384
	ds_read_b128 v[188:191], v145 offset:17408
	ds_read_b128 v[206:209], v145 offset:18432
	ds_read_b128 v[218:221], v145 offset:19456
	ds_read_b128 v[222:225], v145 offset:20480
	ds_read_b128 v[226:229], v145 offset:21504
	ds_read_b128 v[230:233], v145 offset:22528
	ds_read_b128 v[234:237], v145 offset:23552
	global_load_lds_dwordx4 v[194:195], off
	s_add_i32 m0, s50, 0x2000
	s_add_u32 s50, s26, 0x100000
	v_lshl_add_u64 v[210:211], s[26:27], 0, v[132:133]
	s_addc_u32 s51, s27, 0
	s_add_i32 s52, s52, s38
	global_load_lds_dwordx4 v[210:211], off
	v_lshl_add_u64 v[212:213], s[50:51], 0, v[130:131]
	s_mov_b32 m0, s52
	v_lshl_add_u64 v[238:239], s[28:29], 0, v[132:133]
	global_load_lds_dwordx4 v[212:213], off
	v_lshl_add_u64 v[212:213], s[50:51], 0, v[132:133]
	s_add_i32 m0, s52, 0x2000
	s_nop 0
	global_load_lds_dwordx4 v[212:213], off
	v_lshl_add_u64 v[212:213], s[28:29], 0, v[130:131]
	s_mov_b32 m0, s23
	s_nop 0
	global_load_lds_dwordx4 v[212:213], off
	s_mov_b32 m0, s39
	s_nop 0
	global_load_lds_dwordx4 v[238:239], off
	s_setprio 1
	s_waitcnt vmcnt(8) lgkmcnt(0)
	s_barrier
; #define PG8_STAGE(bufoff, gbase, voff) do { _Pragma("unroll") for (int _i = 0; _i < 2; ++_i) \
;         __builtin_amdgcn_global_load_lds((const unsigned*)((const char*)(gbase) + (voff)[_i]), (PG8_LAS unsigned*)(lds + (bufoff) + ldsw + _i * 8192), 16, 0, 0); } while (0)
; #define PG8_LDA(dst, b, h) do { _Pragma("unroll") for (int m = 0; m < 4; ++m) _Pragma("unroll") for (int k = 0; k < 2; ++k) dst[m][k] = *(const PG8_LAS bf16x8*)(lds + PG8_SA(b, h) + aoff + m * 2048 + k * 1024); } while (0)
; #define PG8_LDB(dst, b, h) do { _Pragma("unroll") for (int n = 0; n < 2; ++n) _Pragma("unroll") for (int k = 0; k < 2; ++k) dst[n][k] = *(const PG8_LAS bf16x8*)(lds + PG8_SB(b, h) + boff + n * 2048 + k * 1024); } while (0)
; #define PG8_MMA(ai, bj, At, Bt) do { __builtin_amdgcn_s_setprio(1); _Pragma("unroll") for (int m = 0; m < 4; ++m) _Pragma("unroll") for (int n = 0; n < 2; ++n) _Pragma("unroll") for (int k = 0; k < 2; ++k) \
;         acc[ai][bj][m][n] = __builtin_amdgcn_mfma_f32_16x16x32_bf16(Bt[n][k], At[m][k], acc[ai][bj][m][n], 0, 0, 0); __builtin_amdgcn_s_setprio(0); } while (0)
; #define PG8_WAIT_V(n) asm volatile("s_waitcnt vmcnt(" #n ")" ::: "memory")
; #define PG8_WAIT_L(n) asm volatile("s_waitcnt lgkmcnt(" #n ")" ::: "memory")
; #define PG8_BAR __builtin_amdgcn_s_barrier()
; #define PG8_SCHED __builtin_amdgcn_sched_barrier(0)
; template <class Epi, class Sched, bool ALIGN_EPI, int LMASK = -1, int LMASKB = LMASK>
; __device__ __forceinline__ void gemm_phase(PG8_LAS unsigned char* lds, const Gemm g, const Sched& S, const Epi& E) {
;     ...
;             PG8_WAIT_V(8); PG8_WAIT_L(0); PG8_BAR; PG8_MMA(1, 0, At, B0); PG8_MMA(1, 1, At, B1); PG8_BAR; PG8_SCHED;
;             PG8_LDB(B0, 1, 0); PG8_LDB(B1, 1, 1); PG8_SCHED; PG8_LDA(At, 1, 0); PG8_STAGE(PG8_SA(0, 1), a2 + hstepA, voffA);
;             PG8_WAIT_V(8); PG8_WAIT_L(0); PG8_BAR; PG8_MMA(0, 0, At, B0); PG8_MMA(0, 1, At, B1); PG8_BAR; PG8_SCHED;
;             PG8_LDA(At, 1, 1); PG8_STAGE(PG8_SB(1, 0), b3, voffB); PG8_STAGE(PG8_SB(1, 1), b3 + hstepB, voffB); PG8_STAGE(PG8_SA(1, 0), a3, voffA);
	v_mfma_f32_16x16x32_bf16 v[62:65], v[138:141], v[174:177], v[62:65]
	v_mfma_f32_16x16x32_bf16 v[58:61], v[150:153], v[174:177], v[58:61]
	v_mfma_f32_16x16x32_bf16 v[46:49], v[138:141], v[206:209], v[46:49]
	v_mfma_f32_16x16x32_bf16 v[42:45], v[150:153], v[206:209], v[42:45]
	v_mfma_f32_16x16x32_bf16 v[30:33], v[138:141], v[222:225], v[30:33]
	v_mfma_f32_16x16x32_bf16 v[26:29], v[150:153], v[222:225], v[26:29]
	v_mfma_f32_16x16x32_bf16 v[14:17], v[138:141], v[230:233], v[14:17]
	v_mfma_f32_16x16x32_bf16 v[10:13], v[150:153], v[230:233], v[10:13]
	v_mfma_f32_16x16x32_bf16 v[62:65], v[146:149], v[188:191], v[62:65]
	v_mfma_f32_16x16x32_bf16 v[58:61], v[154:157], v[188:191], v[58:61]
	v_mfma_f32_16x16x32_bf16 v[46:49], v[146:149], v[218:221], v[46:49]
	v_mfma_f32_16x16x32_bf16 v[42:45], v[154:157], v[218:221], v[42:45]
	v_mfma_f32_16x16x32_bf16 v[30:33], v[146:149], v[226:229], v[30:33]
	v_mfma_f32_16x16x32_bf16 v[26:29], v[154:157], v[226:229], v[26:29]
	v_mfma_f32_16x16x32_bf16 v[14:17], v[146:149], v[234:237], v[14:17]
	v_mfma_f32_16x16x32_bf16 v[10:13], v[154:157], v[234:237], v[10:13]
	v_mfma_f32_16x16x32_bf16 v[54:57], v[158:161], v[174:177], v[54:57]
	v_mfma_f32_16x16x32_bf16 v[50:53], v[166:169], v[174:177], v[50:53]
	v_mfma_f32_16x16x32_bf16 v[38:41], v[158:161], v[206:209], v[38:41]
	v_mfma_f32_16x16x32_bf16 v[34:37], v[166:169], v[206:209], v[34:37]
	v_mfma_f32_16x16x32_bf16 v[22:25], v[158:161], v[222:225], v[22:25]
	v_mfma_f32_16x16x32_bf16 v[18:21], v[166:169], v[222:225], v[18:21]
	v_mfma_f32_16x16x32_bf16 v[6:9], v[158:161], v[230:233], v[6:9]
	v_mfma_f32_16x16x32_bf16 v[2:5], v[166:169], v[230:233], v[2:5]
	v_mfma_f32_16x16x32_bf16 v[54:57], v[162:165], v[188:191], v[54:57]
	v_mfma_f32_16x16x32_bf16 v[50:53], v[170:173], v[188:191], v[50:53]
	v_mfma_f32_16x16x32_bf16 v[38:41], v[162:165], v[218:221], v[38:41]
	v_mfma_f32_16x16x32_bf16 v[34:37], v[170:173], v[218:221], v[34:37]
	v_mfma_f32_16x16x32_bf16 v[22:25], v[162:165], v[226:229], v[22:25]
	v_mfma_f32_16x16x32_bf16 v[18:21], v[170:173], v[226:229], v[18:21]
	v_mfma_f32_16x16x32_bf16 v[6:9], v[162:165], v[234:237], v[6:9]
	v_mfma_f32_16x16x32_bf16 v[2:5], v[170:173], v[234:237], v[2:5]
	s_barrier
	s_setprio 0
	s_add_i32 s50, 0, 0x18000
	s_add_i32 s51, 0, 0x1c000
	v_add_u32_e32 v154, s50, v143
	v_add_u32_e32 v170, s51, v143
	ds_read_b128 v[138:141], v154
	ds_read_b128 v[146:149], v154 offset:1024
	ds_read_b128 v[150:153], v154 offset:2048
	ds_read_b128 v[154:157], v154 offset:3072
	ds_read_b128 v[158:161], v170
	ds_read_b128 v[162:165], v170 offset:1024
	ds_read_b128 v[166:169], v170 offset:2048
	ds_read_b128 v[170:173], v170 offset:3072
	s_add_u32 s28, s28, 0x100000
	s_addc_u32 s29, s29, 0
	s_mov_b32 m0, s40
	v_lshl_add_u64 v[240:241], s[28:29], 0, v[130:131]
	ds_read_b128 v[174:177], v145 offset:32768
	ds_read_b128 v[188:191], v145 offset:33792
	ds_read_b128 v[206:209], v145 offset:34816
	ds_read_b128 v[218:221], v145 offset:35840
	ds_read_b128 v[222:225], v145 offset:36864
	ds_read_b128 v[226:229], v145 offset:37888
	ds_read_b128 v[230:233], v145 offset:38912
	ds_read_b128 v[234:237], v145 offset:39936
	global_load_lds_dwordx4 v[240:241], off
	v_lshl_add_u64 v[240:241], s[28:29], 0, v[132:133]
	s_mov_b32 m0, s41
	s_nop 0
	global_load_lds_dwordx4 v[240:241], off
	s_setprio 1
	s_waitcnt vmcnt(8) lgkmcnt(0)
	s_barrier
	v_mfma_f32_16x16x32_bf16 v[126:129], v[138:141], v[174:177], v[126:129]
	v_mfma_f32_16x16x32_bf16 v[122:125], v[150:153], v[174:177], v[122:125]
	v_mfma_f32_16x16x32_bf16 v[110:113], v[138:141], v[206:209], v[110:113]
	v_mfma_f32_16x16x32_bf16 v[106:109], v[150:153], v[206:209], v[106:109]
	v_mfma_f32_16x16x32_bf16 v[94:97], v[138:141], v[222:225], v[94:97]
	v_mfma_f32_16x16x32_bf16 v[90:93], v[150:153], v[222:225], v[90:93]
	v_mfma_f32_16x16x32_bf16 v[78:81], v[138:141], v[230:233], v[78:81]
	v_mfma_f32_16x16x32_bf16 v[74:77], v[150:153], v[230:233], v[74:77]
	v_mfma_f32_16x16x32_bf16 v[126:129], v[146:149], v[188:191], v[126:129]
	v_mfma_f32_16x16x32_bf16 v[122:125], v[154:157], v[188:191], v[122:125]
	v_mfma_f32_16x16x32_bf16 v[110:113], v[146:149], v[218:221], v[110:113]
	v_mfma_f32_16x16x32_bf16 v[106:109], v[154:157], v[218:221], v[106:109]
	v_mfma_f32_16x16x32_bf16 v[94:97], v[146:149], v[226:229], v[94:97]
	v_mfma_f32_16x16x32_bf16 v[90:93], v[154:157], v[226:229], v[90:93]
	v_mfma_f32_16x16x32_bf16 v[78:81], v[146:149], v[234:237], v[78:81]
	v_mfma_f32_16x16x32_bf16 v[74:77], v[154:157], v[234:237], v[74:77]
	v_mfma_f32_16x16x32_bf16 v[118:121], v[158:161], v[174:177], v[118:121]
	v_mfma_f32_16x16x32_bf16 v[114:117], v[166:169], v[174:177], v[114:117]
	v_mfma_f32_16x16x32_bf16 v[102:105], v[158:161], v[206:209], v[102:105]
	v_mfma_f32_16x16x32_bf16 v[98:101], v[166:169], v[206:209], v[98:101]
	v_mfma_f32_16x16x32_bf16 v[86:89], v[158:161], v[222:225], v[86:89]
	v_mfma_f32_16x16x32_bf16 v[82:85], v[166:169], v[222:225], v[82:85]
	v_mfma_f32_16x16x32_bf16 v[70:73], v[158:161], v[230:233], v[70:73]
	v_mfma_f32_16x16x32_bf16 v[66:69], v[166:169], v[230:233], v[66:69]
	v_mfma_f32_16x16x32_bf16 v[118:121], v[162:165], v[188:191], v[118:121]
	v_mfma_f32_16x16x32_bf16 v[114:117], v[170:173], v[188:191], v[114:117]
	v_mfma_f32_16x16x32_bf16 v[102:105], v[162:165], v[218:221], v[102:105]
	v_mfma_f32_16x16x32_bf16 v[98:101], v[170:173], v[218:221], v[98:101]
	v_mfma_f32_16x16x32_bf16 v[86:89], v[162:165], v[226:229], v[86:89]
	v_mfma_f32_16x16x32_bf16 v[82:85], v[170:173], v[226:229], v[82:85]
	v_mfma_f32_16x16x32_bf16 v[70:73], v[162:165], v[234:237], v[70:73]
	v_mfma_f32_16x16x32_bf16 v[66:69], v[170:173], v[234:237], v[66:69]
	s_barrier
; #define PG8_STAGE(bufoff, gbase, voff) do { _Pragma("unroll") for (int _i = 0; _i < 2; ++_i) \
;         __builtin_amdgcn_global_load_lds((const unsigned*)((const char*)(gbase) + (voff)[_i]), (PG8_LAS unsigned*)(lds + (bufoff) + ldsw + _i * 8192), 16, 0, 0); } while (0)
; #define PG8_LDA(dst, b, h) do { _Pragma("unroll") for (int m = 0; m < 4; ++m) _Pragma("unroll") for (int k = 0; k < 2; ++k) dst[m][k] = *(const PG8_LAS bf16x8*)(lds + PG8_SA(b, h) + aoff + m * 2048 + k * 1024); } while (0)
; #define PG8_MMA(ai, bj, At, Bt) do { __builtin_amdgcn_s_setprio(1); _Pragma("unroll") for (int m = 0; m < 4; ++m) _Pragma("unroll") for (int n = 0; n < 2; ++n) _Pragma("unroll") for (int k = 0; k < 2; ++k) \
;         acc[ai][bj][m][n] = __builtin_amdgcn_mfma_f32_16x16x32_bf16(Bt[n][k], At[m][k], acc[ai][bj][m][n], 0, 0, 0); __builtin_amdgcn_s_setprio(0); } while (0)
; #define PG8_WAIT_V(n) asm volatile("s_waitcnt vmcnt(" #n ")" ::: "memory")
; #define PG8_WAIT_L(n) asm volatile("s_waitcnt lgkmcnt(" #n ")" ::: "memory")
; #define PG8_BAR __builtin_amdgcn_s_barrier()
; #define PG8_SCHED __builtin_amdgcn_sched_barrier(0)
; template <class Epi, class Sched, bool ALIGN_EPI, int LMASK = -1, int LMASKB = LMASK>
; __device__ __forceinline__ void gemm_phase(PG8_LAS unsigned char* lds, const Gemm g, const Sched& S, const Epi& E) {
;     ...
;             PG8_LDA(At, 1, 1); PG8_STAGE(PG8_SB(1, 0), b3, voffB); PG8_STAGE(PG8_SB(1, 1), b3 + hstepB, voffB); PG8_STAGE(PG8_SA(1, 0), a3, voffA);
;             PG8_WAIT_V(8); PG8_WAIT_L(0); PG8_BAR; PG8_MMA(1, 0, At, B0); PG8_MMA(1, 1, At, B1); PG8_BAR; PG8_SCHED;
;         }
;         if constexpr (ALIGN_EPI) { if (wr == 0) PG8_BAR; }
	s_setprio 0
	s_add_i32 s28, s50, s38
	v_lshl_add_u64 v[194:195], v[194:195], 0, s[80:81]
	s_mov_b32 m0, s28
	ds_read_b128 v[174:177], v145 offset:49152
	ds_read_b128 v[188:191], v145 offset:50176
	ds_read_b128 v[206:209], v145 offset:51200
	ds_read_b128 v[218:221], v145 offset:52224
	ds_read_b128 v[222:225], v145 offset:53248
	ds_read_b128 v[226:229], v145 offset:54272
	ds_read_b128 v[230:233], v145 offset:55296
	ds_read_b128 v[234:237], v145 offset:56320
	global_load_lds_dwordx4 v[194:195], off
	s_add_i32 m0, s28, 0x2000
	s_add_u32 s26, s26, 0x100800
	v_lshl_add_u64 v[194:195], v[210:211], 0, s[80:81]
	s_addc_u32 s27, s27, 0
	s_add_i32 s28, s51, s38
	global_load_lds_dwordx4 v[194:195], off
	v_lshl_add_u64 v[194:195], s[26:27], 0, v[130:131]
	s_mov_b32 m0, s28
	s_nop 0
	global_load_lds_dwordx4 v[194:195], off
	v_lshl_add_u64 v[194:195], s[26:27], 0, v[132:133]
	s_add_i32 m0, s28, 0x2000
	s_nop 0
	global_load_lds_dwordx4 v[194:195], off
	v_lshl_add_u64 v[194:195], v[212:213], 0, s[80:81]
	s_mov_b32 m0, s42
	s_nop 0
	global_load_lds_dwordx4 v[194:195], off
	v_lshl_add_u64 v[194:195], v[238:239], 0, s[80:81]
	s_mov_b32 m0, s43
	s_nop 0
	global_load_lds_dwordx4 v[194:195], off
	s_setprio 1
	s_waitcnt vmcnt(8) lgkmcnt(0)
	s_barrier
	v_mfma_f32_16x16x32_bf16 v[62:65], v[138:141], v[174:177], v[62:65]
	v_mfma_f32_16x16x32_bf16 v[58:61], v[150:153], v[174:177], v[58:61]
	v_mfma_f32_16x16x32_bf16 v[46:49], v[138:141], v[206:209], v[46:49]
	v_mfma_f32_16x16x32_bf16 v[42:45], v[150:153], v[206:209], v[42:45]
	v_mfma_f32_16x16x32_bf16 v[30:33], v[138:141], v[222:225], v[30:33]
	v_mfma_f32_16x16x32_bf16 v[26:29], v[150:153], v[222:225], v[26:29]
	v_mfma_f32_16x16x32_bf16 v[14:17], v[138:141], v[230:233], v[14:17]
	v_mfma_f32_16x16x32_bf16 v[10:13], v[150:153], v[230:233], v[10:13]
	v_mfma_f32_16x16x32_bf16 v[62:65], v[146:149], v[188:191], v[62:65]
	v_mfma_f32_16x16x32_bf16 v[58:61], v[154:157], v[188:191], v[58:61]
	v_mfma_f32_16x16x32_bf16 v[46:49], v[146:149], v[218:221], v[46:49]
	v_mfma_f32_16x16x32_bf16 v[42:45], v[154:157], v[218:221], v[42:45]
	v_mfma_f32_16x16x32_bf16 v[30:33], v[146:149], v[226:229], v[30:33]
	v_mfma_f32_16x16x32_bf16 v[26:29], v[154:157], v[226:229], v[26:29]
	v_mfma_f32_16x16x32_bf16 v[14:17], v[146:149], v[234:237], v[14:17]
	v_mfma_f32_16x16x32_bf16 v[10:13], v[154:157], v[234:237], v[10:13]
	v_mfma_f32_16x16x32_bf16 v[54:57], v[158:161], v[174:177], v[54:57]
	v_mfma_f32_16x16x32_bf16 v[50:53], v[166:169], v[174:177], v[50:53]
	v_mfma_f32_16x16x32_bf16 v[38:41], v[158:161], v[206:209], v[38:41]
	v_mfma_f32_16x16x32_bf16 v[34:37], v[166:169], v[206:209], v[34:37]
	v_mfma_f32_16x16x32_bf16 v[22:25], v[158:161], v[222:225], v[22:25]
	v_mfma_f32_16x16x32_bf16 v[18:21], v[166:169], v[222:225], v[18:21]
	v_mfma_f32_16x16x32_bf16 v[6:9], v[158:161], v[230:233], v[6:9]
	v_mfma_f32_16x16x32_bf16 v[2:5], v[166:169], v[230:233], v[2:5]
	v_mfma_f32_16x16x32_bf16 v[54:57], v[162:165], v[188:191], v[54:57]
	v_mfma_f32_16x16x32_bf16 v[50:53], v[170:173], v[188:191], v[50:53]
	v_mfma_f32_16x16x32_bf16 v[38:41], v[162:165], v[218:221], v[38:41]
	v_mfma_f32_16x16x32_bf16 v[34:37], v[170:173], v[218:221], v[34:37]
	v_mfma_f32_16x16x32_bf16 v[22:25], v[162:165], v[226:229], v[22:25]
	v_mfma_f32_16x16x32_bf16 v[18:21], v[170:173], v[226:229], v[18:21]
	v_mfma_f32_16x16x32_bf16 v[6:9], v[162:165], v[234:237], v[6:9]
	v_mfma_f32_16x16x32_bf16 v[2:5], v[170:173], v[234:237], v[2:5]
	s_barrier
	s_setprio 0
	s_add_i32 s49, s49, 2
	s_add_u32 s24, s24, 0x1000
	s_addc_u32 s25, s25, 0
	s_add_u32 s47, s47, 0x1000
	s_addc_u32 s48, s48, 0
	s_cmp_gt_u32 s49, 61
	s_cbranch_scc0 .LBB0_678
	s_and_b64 vcc, exec, s[12:13]
	s_cbranch_vccz .LBB0_681
	s_barrier

; #define PG8_STAGE(bufoff, gbase, voff) do { _Pragma("unroll") for (int _i = 0; _i < 2; ++_i) \
;         __builtin_amdgcn_global_load_lds((const unsigned*)((const char*)(gbase) + (voff)[_i]), (PG8_LAS unsigned*)(lds + (bufoff) + ldsw + _i * 8192), 16, 0, 0); } while (0)
; #define PG8_LDA(dst, b, h) do { _Pragma("unroll") for (int m = 0; m < 4; ++m) _Pragma("unroll") for (int k = 0; k < 2; ++k) dst[m][k] = *(const PG8_LAS bf16x8*)(lds + PG8_SA(b, h) + aoff + m * 2048 + k * 1024); } while (0)
; #define PG8_LDB(dst, b, h) do { _Pragma("unroll") for (int n = 0; n < 2; ++n) _Pragma("unroll") for (int k = 0; k < 2; ++k) dst[n][k] = *(const PG8_LAS bf16x8*)(lds + PG8_SB(b, h) + boff + n * 2048 + k * 1024); } while (0)
; #define PG8_MMA(ai, bj, At, Bt) do { __builtin_amdgcn_s_setprio(1); _Pragma("unroll") for (int m = 0; m < 4; ++m) _Pragma("unroll") for (int n = 0; n < 2; ++n) _Pragma("unroll") for (int k = 0; k < 2; ++k) \
;         acc[ai][bj][m][n] = __builtin_amdgcn_mfma_f32_16x16x32_bf16(Bt[n][k], At[m][k], acc[ai][bj][m][n], 0, 0, 0); __builtin_amdgcn_s_setprio(0); } while (0)
; #define PG8_WAIT_V(n) asm volatile("s_waitcnt vmcnt(" #n ")" ::: "memory")
; #define PG8_WAIT_L(n) asm volatile("s_waitcnt lgkmcnt(" #n ")" ::: "memory")
; #define PG8_BAR __builtin_amdgcn_s_barrier()
; #define PG8_SCHED __builtin_amdgcn_sched_barrier(0)
; template <class Epi, class Sched, bool ALIGN_EPI, int LMASK = -1, int LMASKB = LMASK>
; __device__ __forceinline__ void gemm_phase(PG8_LAS unsigned char* lds, const Gemm g, const Sched& S, const Epi& E) {
;     ...
;             PG8_LDB(B0, 0, 0); PG8_LDB(B1, 0, 1); PG8_SCHED; PG8_LDA(At, 0, 0); PG8_STAGE(PG8_SA(1, 1), a1 + hstepA, voffA);
;             PG8_WAIT_V(8); PG8_WAIT_L(0); PG8_BAR; PG8_MMA(0, 0, At, B0); PG8_MMA(0, 1, At, B1); PG8_BAR; PG8_SCHED;
;             PG8_LDA(At, 0, 1); PG8_STAGE(PG8_SB(0, 0), b2, voffB); PG8_STAGE(PG8_SB(0, 1), b2 + hstepB, voffB); PG8_STAGE(PG8_SA(0, 0), a2, voffA);
;             PG8_WAIT_V(8); PG8_WAIT_L(0); PG8_BAR; PG8_MMA(1, 0, At, B0); PG8_MMA(1, 1, At, B1); PG8_BAR; PG8_SCHED;
.LBB0_761:
	s_add_u32 s2, s28, 0xffc00800
	s_addc_u32 s3, s29, -1
	s_add_i32 s51, 0, 0x10000
	s_cmpk_eq_i32 s50, 0xfc
	s_cselect_b32 s31, s19, s3
	s_cselect_b32 s30, s46, s2
	v_add_u32_e32 v146, s51, v149
	s_cselect_b32 s3, s17, s49
	s_cselect_b32 s2, s47, s48
	s_add_i32 s54, 0, 0x14000
	ds_read_b128 v[130:133], v146
	ds_read_b128 v[142:145], v146 offset:1024
	ds_read_b128 v[152:155], v146 offset:2048
	ds_read_b128 v[156:159], v146 offset:3072
	v_add_u32_e32 v146, s54, v149
	ds_read_b128 v[160:163], v146
	ds_read_b128 v[164:167], v146 offset:1024
	ds_read_b128 v[168:171], v146 offset:2048
	ds_read_b128 v[172:175], v146 offset:3072
	v_lshl_add_u64 v[146:147], s[28:29], 0, v[138:139]
	s_add_i32 m0, s25, 0xc000
	ds_read_b128 v[188:191], v151
	ds_read_b128 v[206:209], v151 offset:1024
	ds_read_b128 v[218:221], v151 offset:2048
	ds_read_b128 v[222:225], v151 offset:3072
	ds_read_b128 v[226:229], v151 offset:4096
	ds_read_b128 v[230:233], v151 offset:5120
	ds_read_b128 v[234:237], v151 offset:6144
	ds_read_b128 v[238:241], v151 offset:7168
	global_load_lds_dwordx4 v[146:147], off
	v_lshl_add_u64 v[146:147], s[28:29], 0, v[140:141]
	s_add_i32 m0, s25, 0xe000
	s_nop 0
	global_load_lds_dwordx4 v[146:147], off
	s_setprio 1
	s_waitcnt vmcnt(8) lgkmcnt(0)
	s_barrier
	v_mfma_f32_16x16x32_bf16 v[126:129], v[130:133], v[188:191], v[126:129]
	v_mfma_f32_16x16x32_bf16 v[122:125], v[152:155], v[188:191], v[122:125]
	v_mfma_f32_16x16x32_bf16 v[110:113], v[130:133], v[218:221], v[110:113]
	v_mfma_f32_16x16x32_bf16 v[106:109], v[152:155], v[218:221], v[106:109]
	v_mfma_f32_16x16x32_bf16 v[94:97], v[130:133], v[226:229], v[94:97]
	v_mfma_f32_16x16x32_bf16 v[90:93], v[152:155], v[226:229], v[90:93]
	v_mfma_f32_16x16x32_bf16 v[78:81], v[130:133], v[234:237], v[78:81]
	v_mfma_f32_16x16x32_bf16 v[74:77], v[152:155], v[234:237], v[74:77]
	v_mfma_f32_16x16x32_bf16 v[126:129], v[142:145], v[206:209], v[126:129]
	v_mfma_f32_16x16x32_bf16 v[122:125], v[156:159], v[206:209], v[122:125]
	v_mfma_f32_16x16x32_bf16 v[110:113], v[142:145], v[222:225], v[110:113]
	v_mfma_f32_16x16x32_bf16 v[106:109], v[156:159], v[222:225], v[106:109]
	v_mfma_f32_16x16x32_bf16 v[94:97], v[142:145], v[230:233], v[94:97]
	v_mfma_f32_16x16x32_bf16 v[90:93], v[156:159], v[230:233], v[90:93]
	v_mfma_f32_16x16x32_bf16 v[78:81], v[142:145], v[238:241], v[78:81]
	v_mfma_f32_16x16x32_bf16 v[74:77], v[156:159], v[238:241], v[74:77]
	v_mfma_f32_16x16x32_bf16 v[118:121], v[160:163], v[188:191], v[118:121]
	v_mfma_f32_16x16x32_bf16 v[114:117], v[168:171], v[188:191], v[114:117]
	v_mfma_f32_16x16x32_bf16 v[102:105], v[160:163], v[218:221], v[102:105]
	v_mfma_f32_16x16x32_bf16 v[98:101], v[168:171], v[218:221], v[98:101]
	v_mfma_f32_16x16x32_bf16 v[86:89], v[160:163], v[226:229], v[86:89]
	v_mfma_f32_16x16x32_bf16 v[82:85], v[168:171], v[226:229], v[82:85]
	v_mfma_f32_16x16x32_bf16 v[70:73], v[160:163], v[234:237], v[70:73]
	v_mfma_f32_16x16x32_bf16 v[66:69], v[168:171], v[234:237], v[66:69]
	v_mfma_f32_16x16x32_bf16 v[118:121], v[164:167], v[206:209], v[118:121]
	v_mfma_f32_16x16x32_bf16 v[114:117], v[172:175], v[206:209], v[114:117]
	v_mfma_f32_16x16x32_bf16 v[102:105], v[164:167], v[222:225], v[102:105]
	v_mfma_f32_16x16x32_bf16 v[98:101], v[172:175], v[222:225], v[98:101]
	v_mfma_f32_16x16x32_bf16 v[86:89], v[164:167], v[230:233], v[86:89]
	v_mfma_f32_16x16x32_bf16 v[82:85], v[172:175], v[230:233], v[82:85]
	v_mfma_f32_16x16x32_bf16 v[70:73], v[164:167], v[238:241], v[70:73]
	v_mfma_f32_16x16x32_bf16 v[66:69], v[172:175], v[238:241], v[66:69]
	s_barrier
	s_setprio 0
	s_add_i32 s51, s51, s38
	v_lshl_add_u64 v[146:147], s[2:3], 0, v[134:135]
	s_mov_b32 m0, s51
	ds_read_b128 v[188:191], v151 offset:16384
	ds_read_b128 v[206:209], v151 offset:17408
	ds_read_b128 v[218:221], v151 offset:18432
	ds_read_b128 v[222:225], v151 offset:19456
	ds_read_b128 v[226:229], v151 offset:20480
	ds_read_b128 v[230:233], v151 offset:21504
	ds_read_b128 v[234:237], v151 offset:22528
	ds_read_b128 v[238:241], v151 offset:23552
	global_load_lds_dwordx4 v[146:147], off
	s_add_i32 m0, s51, 0x2000
	s_add_u32 s52, s2, 0x400000
	v_lshl_add_u64 v[176:177], s[2:3], 0, v[136:137]
	s_addc_u32 s53, s3, 0
	s_add_i32 s51, s54, s38
	global_load_lds_dwordx4 v[176:177], off
	v_lshl_add_u64 v[194:195], s[52:53], 0, v[134:135]
	s_mov_b32 m0, s51
	v_lshl_add_u64 v[210:211], s[30:31], 0, v[136:137]
	global_load_lds_dwordx4 v[194:195], off
	v_lshl_add_u64 v[194:195], s[52:53], 0, v[136:137]
	s_add_i32 m0, s51, 0x2000
	s_nop 0
	global_load_lds_dwordx4 v[194:195], off
	v_lshl_add_u64 v[194:195], s[30:31], 0, v[134:135]
	s_mov_b32 m0, s25
	s_nop 0
	global_load_lds_dwordx4 v[194:195], off
	s_mov_b32 m0, s27
	s_nop 0
	global_load_lds_dwordx4 v[210:211], off
	s_setprio 1
	s_waitcnt vmcnt(8) lgkmcnt(0)
	s_barrier
; #define PG8_STAGE(bufoff, gbase, voff) do { _Pragma("unroll") for (int _i = 0; _i < 2; ++_i) \
;         __builtin_amdgcn_global_load_lds((const unsigned*)((const char*)(gbase) + (voff)[_i]), (PG8_LAS unsigned*)(lds + (bufoff) + ldsw + _i * 8192), 16, 0, 0); } while (0)
; #define PG8_LDA(dst, b, h) do { _Pragma("unroll") for (int m = 0; m < 4; ++m) _Pragma("unroll") for (int k = 0; k < 2; ++k) dst[m][k] = *(const PG8_LAS bf16x8*)(lds + PG8_SA(b, h) + aoff + m * 2048 + k * 1024); } while (0)
; #define PG8_LDB(dst, b, h) do { _Pragma("unroll") for (int n = 0; n < 2; ++n) _Pragma("unroll") for (int k = 0; k < 2; ++k) dst[n][k] = *(const PG8_LAS bf16x8*)(lds + PG8_SB(b, h) + boff + n * 2048 + k * 1024); } while (0)
; #define PG8_MMA(ai, bj, At, Bt) do { __builtin_amdgcn_s_setprio(1); _Pragma("unroll") for (int m = 0; m < 4; ++m) _Pragma("unroll") for (int n = 0; n < 2; ++n) _Pragma("unroll") for (int k = 0; k < 2; ++k) \
;         acc[ai][bj][m][n] = __builtin_amdgcn_mfma_f32_16x16x32_bf16(Bt[n][k], At[m][k], acc[ai][bj][m][n], 0, 0, 0); __builtin_amdgcn_s_setprio(0); } while (0)
; #define PG8_WAIT_V(n) asm volatile("s_waitcnt vmcnt(" #n ")" ::: "memory")
; #define PG8_WAIT_L(n) asm volatile("s_waitcnt lgkmcnt(" #n ")" ::: "memory")
; #define PG8_BAR __builtin_amdgcn_s_barrier()
; #define PG8_SCHED __builtin_amdgcn_sched_barrier(0)
; template <class Epi, class Sched, bool ALIGN_EPI, int LMASK = -1, int LMASKB = LMASK>
; __device__ __forceinline__ void gemm_phase(PG8_LAS unsigned char* lds, const Gemm g, const Sched& S, const Epi& E) {
;     ...
;             PG8_WAIT_V(8); PG8_WAIT_L(0); PG8_BAR; PG8_MMA(1, 0, At, B0); PG8_MMA(1, 1, At, B1); PG8_BAR; PG8_SCHED;
;             PG8_LDB(B0, 1, 0); PG8_LDB(B1, 1, 1); PG8_SCHED; PG8_LDA(At, 1, 0); PG8_STAGE(PG8_SA(0, 1), a2 + hstepA, voffA);
;             PG8_WAIT_V(8); PG8_WAIT_L(0); PG8_BAR; PG8_MMA(0, 0, At, B0); PG8_MMA(0, 1, At, B1); PG8_BAR; PG8_SCHED;
;             PG8_LDA(At, 1, 1); PG8_STAGE(PG8_SB(1, 0), b3, voffB); PG8_STAGE(PG8_SB(1, 1), b3 + hstepB, voffB); PG8_STAGE(PG8_SA(1, 0), a3, voffA);
	v_mfma_f32_16x16x32_bf16 v[62:65], v[130:133], v[188:191], v[62:65]
	v_mfma_f32_16x16x32_bf16 v[58:61], v[152:155], v[188:191], v[58:61]
	v_mfma_f32_16x16x32_bf16 v[46:49], v[130:133], v[218:221], v[46:49]
	v_mfma_f32_16x16x32_bf16 v[42:45], v[152:155], v[218:221], v[42:45]
	v_mfma_f32_16x16x32_bf16 v[30:33], v[130:133], v[226:229], v[30:33]
	v_mfma_f32_16x16x32_bf16 v[26:29], v[152:155], v[226:229], v[26:29]
	v_mfma_f32_16x16x32_bf16 v[14:17], v[130:133], v[234:237], v[14:17]
	v_mfma_f32_16x16x32_bf16 v[10:13], v[152:155], v[234:237], v[10:13]
	v_mfma_f32_16x16x32_bf16 v[62:65], v[142:145], v[206:209], v[62:65]
	v_mfma_f32_16x16x32_bf16 v[58:61], v[156:159], v[206:209], v[58:61]
	v_mfma_f32_16x16x32_bf16 v[46:49], v[142:145], v[222:225], v[46:49]
	v_mfma_f32_16x16x32_bf16 v[42:45], v[156:159], v[222:225], v[42:45]
	v_mfma_f32_16x16x32_bf16 v[30:33], v[142:145], v[230:233], v[30:33]
	v_mfma_f32_16x16x32_bf16 v[26:29], v[156:159], v[230:233], v[26:29]
	v_mfma_f32_16x16x32_bf16 v[14:17], v[142:145], v[238:241], v[14:17]
	v_mfma_f32_16x16x32_bf16 v[10:13], v[156:159], v[238:241], v[10:13]
	v_mfma_f32_16x16x32_bf16 v[54:57], v[160:163], v[188:191], v[54:57]
	v_mfma_f32_16x16x32_bf16 v[50:53], v[168:171], v[188:191], v[50:53]
	v_mfma_f32_16x16x32_bf16 v[38:41], v[160:163], v[218:221], v[38:41]
	v_mfma_f32_16x16x32_bf16 v[34:37], v[168:171], v[218:221], v[34:37]
	v_mfma_f32_16x16x32_bf16 v[22:25], v[160:163], v[226:229], v[22:25]
	v_mfma_f32_16x16x32_bf16 v[18:21], v[168:171], v[226:229], v[18:21]
	v_mfma_f32_16x16x32_bf16 v[6:9], v[160:163], v[234:237], v[6:9]
	v_mfma_f32_16x16x32_bf16 v[2:5], v[168:171], v[234:237], v[2:5]
	v_mfma_f32_16x16x32_bf16 v[54:57], v[164:167], v[206:209], v[54:57]
	v_mfma_f32_16x16x32_bf16 v[50:53], v[172:175], v[206:209], v[50:53]
	v_mfma_f32_16x16x32_bf16 v[38:41], v[164:167], v[222:225], v[38:41]
	v_mfma_f32_16x16x32_bf16 v[34:37], v[172:175], v[222:225], v[34:37]
	v_mfma_f32_16x16x32_bf16 v[22:25], v[164:167], v[230:233], v[22:25]
	v_mfma_f32_16x16x32_bf16 v[18:21], v[172:175], v[230:233], v[18:21]
	v_mfma_f32_16x16x32_bf16 v[6:9], v[164:167], v[238:241], v[6:9]
	v_mfma_f32_16x16x32_bf16 v[2:5], v[172:175], v[238:241], v[2:5]
	s_barrier
	s_setprio 0
	s_add_i32 s51, 0, 0x18000
	s_add_i32 s52, 0, 0x1c000
	v_add_u32_e32 v156, s51, v149
	v_add_u32_e32 v172, s52, v149
	ds_read_b128 v[130:133], v156
	ds_read_b128 v[142:145], v156 offset:1024
	ds_read_b128 v[152:155], v156 offset:2048
	ds_read_b128 v[156:159], v156 offset:3072
	ds_read_b128 v[160:163], v172
	ds_read_b128 v[164:167], v172 offset:1024
	ds_read_b128 v[168:171], v172 offset:2048
	ds_read_b128 v[172:175], v172 offset:3072
	s_add_u32 s30, s30, 0x400000
	s_addc_u32 s31, s31, 0
	s_mov_b32 m0, s39
	v_lshl_add_u64 v[212:213], s[30:31], 0, v[134:135]
	ds_read_b128 v[188:191], v151 offset:32768
	ds_read_b128 v[206:209], v151 offset:33792
	ds_read_b128 v[218:221], v151 offset:34816
	ds_read_b128 v[222:225], v151 offset:35840
	ds_read_b128 v[226:229], v151 offset:36864
	ds_read_b128 v[230:233], v151 offset:37888
	ds_read_b128 v[234:237], v151 offset:38912
	ds_read_b128 v[238:241], v151 offset:39936
	global_load_lds_dwordx4 v[212:213], off
	v_lshl_add_u64 v[212:213], s[30:31], 0, v[136:137]
	s_mov_b32 m0, s40
	s_nop 0
	global_load_lds_dwordx4 v[212:213], off
	s_setprio 1
	s_waitcnt vmcnt(8) lgkmcnt(0)
	s_barrier
	v_mfma_f32_16x16x32_bf16 v[126:129], v[130:133], v[188:191], v[126:129]
	v_mfma_f32_16x16x32_bf16 v[122:125], v[152:155], v[188:191], v[122:125]
	v_mfma_f32_16x16x32_bf16 v[110:113], v[130:133], v[218:221], v[110:113]
	v_mfma_f32_16x16x32_bf16 v[106:109], v[152:155], v[218:221], v[106:109]
	v_mfma_f32_16x16x32_bf16 v[94:97], v[130:133], v[226:229], v[94:97]
	v_mfma_f32_16x16x32_bf16 v[90:93], v[152:155], v[226:229], v[90:93]
	v_mfma_f32_16x16x32_bf16 v[78:81], v[130:133], v[234:237], v[78:81]
	v_mfma_f32_16x16x32_bf16 v[74:77], v[152:155], v[234:237], v[74:77]
	v_mfma_f32_16x16x32_bf16 v[126:129], v[142:145], v[206:209], v[126:129]
	v_mfma_f32_16x16x32_bf16 v[122:125], v[156:159], v[206:209], v[122:125]
	v_mfma_f32_16x16x32_bf16 v[110:113], v[142:145], v[222:225], v[110:113]
	v_mfma_f32_16x16x32_bf16 v[106:109], v[156:159], v[222:225], v[106:109]
	v_mfma_f32_16x16x32_bf16 v[94:97], v[142:145], v[230:233], v[94:97]
	v_mfma_f32_16x16x32_bf16 v[90:93], v[156:159], v[230:233], v[90:93]
	v_mfma_f32_16x16x32_bf16 v[78:81], v[142:145], v[238:241], v[78:81]
	v_mfma_f32_16x16x32_bf16 v[74:77], v[156:159], v[238:241], v[74:77]
	v_mfma_f32_16x16x32_bf16 v[118:121], v[160:163], v[188:191], v[118:121]
	v_mfma_f32_16x16x32_bf16 v[114:117], v[168:171], v[188:191], v[114:117]
	v_mfma_f32_16x16x32_bf16 v[102:105], v[160:163], v[218:221], v[102:105]
	v_mfma_f32_16x16x32_bf16 v[98:101], v[168:171], v[218:221], v[98:101]
	v_mfma_f32_16x16x32_bf16 v[86:89], v[160:163], v[226:229], v[86:89]
	v_mfma_f32_16x16x32_bf16 v[82:85], v[168:171], v[226:229], v[82:85]
	v_mfma_f32_16x16x32_bf16 v[70:73], v[160:163], v[234:237], v[70:73]
	v_mfma_f32_16x16x32_bf16 v[66:69], v[168:171], v[234:237], v[66:69]
	v_mfma_f32_16x16x32_bf16 v[118:121], v[164:167], v[206:209], v[118:121]
	v_mfma_f32_16x16x32_bf16 v[114:117], v[172:175], v[206:209], v[114:117]
	v_mfma_f32_16x16x32_bf16 v[102:105], v[164:167], v[222:225], v[102:105]
	v_mfma_f32_16x16x32_bf16 v[98:101], v[172:175], v[222:225], v[98:101]
	v_mfma_f32_16x16x32_bf16 v[86:89], v[164:167], v[230:233], v[86:89]
	v_mfma_f32_16x16x32_bf16 v[82:85], v[172:175], v[230:233], v[82:85]
	v_mfma_f32_16x16x32_bf16 v[70:73], v[164:167], v[238:241], v[70:73]
	v_mfma_f32_16x16x32_bf16 v[66:69], v[172:175], v[238:241], v[66:69]
	s_barrier
; #define PG8_STAGE(bufoff, gbase, voff) do { _Pragma("unroll") for (int _i = 0; _i < 2; ++_i) \
;         __builtin_amdgcn_global_load_lds((const unsigned*)((const char*)(gbase) + (voff)[_i]), (PG8_LAS unsigned*)(lds + (bufoff) + ldsw + _i * 8192), 16, 0, 0); } while (0)
; #define PG8_LDA(dst, b, h) do { _Pragma("unroll") for (int m = 0; m < 4; ++m) _Pragma("unroll") for (int k = 0; k < 2; ++k) dst[m][k] = *(const PG8_LAS bf16x8*)(lds + PG8_SA(b, h) + aoff + m * 2048 + k * 1024); } while (0)
; #define PG8_MMA(ai, bj, At, Bt) do { __builtin_amdgcn_s_setprio(1); _Pragma("unroll") for (int m = 0; m < 4; ++m) _Pragma("unroll") for (int n = 0; n < 2; ++n) _Pragma("unroll") for (int k = 0; k < 2; ++k) \
;         acc[ai][bj][m][n] = __builtin_amdgcn_mfma_f32_16x16x32_bf16(Bt[n][k], At[m][k], acc[ai][bj][m][n], 0, 0, 0); __builtin_amdgcn_s_setprio(0); } while (0)
; #define PG8_WAIT_V(n) asm volatile("s_waitcnt vmcnt(" #n ")" ::: "memory")
; #define PG8_WAIT_L(n) asm volatile("s_waitcnt lgkmcnt(" #n ")" ::: "memory")
; #define PG8_BAR __builtin_amdgcn_s_barrier()
; #define PG8_SCHED __builtin_amdgcn_sched_barrier(0)
; template <class Epi, class Sched, bool ALIGN_EPI, int LMASK = -1, int LMASKB = LMASK>
; __device__ __forceinline__ void gemm_phase(PG8_LAS unsigned char* lds, const Gemm g, const Sched& S, const Epi& E) {
;     ...
;             PG8_LDA(At, 1, 1); PG8_STAGE(PG8_SB(1, 0), b3, voffB); PG8_STAGE(PG8_SB(1, 1), b3 + hstepB, voffB); PG8_STAGE(PG8_SA(1, 0), a3, voffA);
;             PG8_WAIT_V(8); PG8_WAIT_L(0); PG8_BAR; PG8_MMA(1, 0, At, B0); PG8_MMA(1, 1, At, B1); PG8_BAR; PG8_SCHED;
;         }
;         if constexpr (ALIGN_EPI) { if (wr == 0) PG8_BAR; }
	s_setprio 0
	s_add_i32 s30, s51, s38
	v_lshl_add_u64 v[146:147], v[146:147], 0, s[80:81]
	s_mov_b32 m0, s30
	ds_read_b128 v[188:191], v151 offset:49152
	ds_read_b128 v[206:209], v151 offset:50176
	ds_read_b128 v[218:221], v151 offset:51200
	ds_read_b128 v[222:225], v151 offset:52224
	ds_read_b128 v[226:229], v151 offset:53248
	ds_read_b128 v[230:233], v151 offset:54272
	ds_read_b128 v[234:237], v151 offset:55296
	ds_read_b128 v[238:241], v151 offset:56320
	global_load_lds_dwordx4 v[146:147], off
	s_add_i32 m0, s30, 0x2000
	s_add_u32 s2, s2, 0x400800
	v_lshl_add_u64 v[146:147], v[176:177], 0, s[80:81]
	s_addc_u32 s3, s3, 0
	s_add_i32 s30, s52, s38
	global_load_lds_dwordx4 v[146:147], off
	v_lshl_add_u64 v[146:147], s[2:3], 0, v[134:135]
	s_mov_b32 m0, s30
	s_nop 0
	global_load_lds_dwordx4 v[146:147], off
	v_lshl_add_u64 v[146:147], s[2:3], 0, v[136:137]
	s_add_i32 m0, s30, 0x2000
	s_nop 0
	global_load_lds_dwordx4 v[146:147], off
	v_lshl_add_u64 v[146:147], v[194:195], 0, s[80:81]
	s_mov_b32 m0, s41
	s_nop 0
	global_load_lds_dwordx4 v[146:147], off
	v_lshl_add_u64 v[146:147], v[210:211], 0, s[80:81]
	s_mov_b32 m0, s42
	s_nop 0
	global_load_lds_dwordx4 v[146:147], off
	s_setprio 1
	s_waitcnt vmcnt(8) lgkmcnt(0)
	s_barrier
	v_mfma_f32_16x16x32_bf16 v[62:65], v[130:133], v[188:191], v[62:65]
	v_mfma_f32_16x16x32_bf16 v[58:61], v[152:155], v[188:191], v[58:61]
	v_mfma_f32_16x16x32_bf16 v[46:49], v[130:133], v[218:221], v[46:49]
	v_mfma_f32_16x16x32_bf16 v[42:45], v[152:155], v[218:221], v[42:45]
	v_mfma_f32_16x16x32_bf16 v[30:33], v[130:133], v[226:229], v[30:33]
	v_mfma_f32_16x16x32_bf16 v[26:29], v[152:155], v[226:229], v[26:29]
	v_mfma_f32_16x16x32_bf16 v[14:17], v[130:133], v[234:237], v[14:17]
	v_mfma_f32_16x16x32_bf16 v[10:13], v[152:155], v[234:237], v[10:13]
	v_mfma_f32_16x16x32_bf16 v[62:65], v[142:145], v[206:209], v[62:65]
	v_mfma_f32_16x16x32_bf16 v[58:61], v[156:159], v[206:209], v[58:61]
	v_mfma_f32_16x16x32_bf16 v[46:49], v[142:145], v[222:225], v[46:49]
	v_mfma_f32_16x16x32_bf16 v[42:45], v[156:159], v[222:225], v[42:45]
	v_mfma_f32_16x16x32_bf16 v[30:33], v[142:145], v[230:233], v[30:33]
	v_mfma_f32_16x16x32_bf16 v[26:29], v[156:159], v[230:233], v[26:29]
	v_mfma_f32_16x16x32_bf16 v[14:17], v[142:145], v[238:241], v[14:17]
	v_mfma_f32_16x16x32_bf16 v[10:13], v[156:159], v[238:241], v[10:13]
	v_mfma_f32_16x16x32_bf16 v[54:57], v[160:163], v[188:191], v[54:57]
	v_mfma_f32_16x16x32_bf16 v[50:53], v[168:171], v[188:191], v[50:53]
	v_mfma_f32_16x16x32_bf16 v[38:41], v[160:163], v[218:221], v[38:41]
	v_mfma_f32_16x16x32_bf16 v[34:37], v[168:171], v[218:221], v[34:37]
	v_mfma_f32_16x16x32_bf16 v[22:25], v[160:163], v[226:229], v[22:25]
	v_mfma_f32_16x16x32_bf16 v[18:21], v[168:171], v[226:229], v[18:21]
	v_mfma_f32_16x16x32_bf16 v[6:9], v[160:163], v[234:237], v[6:9]
	v_mfma_f32_16x16x32_bf16 v[2:5], v[168:171], v[234:237], v[2:5]
	v_mfma_f32_16x16x32_bf16 v[54:57], v[164:167], v[206:209], v[54:57]
	v_mfma_f32_16x16x32_bf16 v[50:53], v[172:175], v[206:209], v[50:53]
	v_mfma_f32_16x16x32_bf16 v[38:41], v[164:167], v[222:225], v[38:41]
	v_mfma_f32_16x16x32_bf16 v[34:37], v[172:175], v[222:225], v[34:37]
	v_mfma_f32_16x16x32_bf16 v[22:25], v[164:167], v[230:233], v[22:25]
	v_mfma_f32_16x16x32_bf16 v[18:21], v[172:175], v[230:233], v[18:21]
	v_mfma_f32_16x16x32_bf16 v[6:9], v[164:167], v[238:241], v[6:9]
	v_mfma_f32_16x16x32_bf16 v[2:5], v[172:175], v[238:241], v[2:5]
	s_barrier
	s_setprio 0
	s_add_i32 s50, s50, 2
	s_add_u32 s28, s28, 0x1000
	s_addc_u32 s29, s29, 0
	s_add_u32 s48, s48, 0x1000
	s_addc_u32 s49, s49, 0
	s_cmpk_gt_u32 s50, 0xfd
	s_cbranch_scc0 .LBB0_761
	s_and_b64 vcc, exec, s[14:15]
	s_cbranch_vccz .LBB0_764
	s_barrier
